# chunk scan: consumer waves load 6 of the 8 M_n MFMA A-fragments straight from global into a 4-deep register ring; loader waves stage only the other 2 through LDS
# speedup vs baseline: 1.0120x; 1.0120x over previous
; #define LAS __attribute__((address_space(3)))
; __device__ __forceinline__ void dn_scan(const Args& a, LAS unsigned char* lds, int wg, int tid, int wave, int lane) {
;     ...
;     for (int u = tid; u < 2 * 8192 / 4; u += NTHR) ((LAS unsigned*)lds)[u] = 0u;
;     if (wave < 4) {
;         f32x16 acc = zero16();
;         ScanB p0, p1, p2, p3, p4, p5, p6, p7;
;         scanb_load(p0, ws, bh, 0, td, te, lane); scanb_load(p1, ws, bh, 1, td, te, lane); scanb_load(p2, ws, bh, 2, td, te, lane); scanb_load(p3, ws, bh, 3, td, te, lane);
;         scanb_load(p4, ws, bh, 4, td, te, lane); scanb_load(p5, ws, bh, 5, td, te, lane); scanb_load(p6, ws, bh, 6, td, te, lane);
;         WG_BAR();
; #pragma unroll 1
;         for (int n = 0; n < NCH; n += 8) {
;             scanb_load(p7, ws, bh, n + 7, td, te, lane);  scan_step(p0, acc, ws, lds, bh, n, 0, td, te, lane); WG_BAR();
;             scanb_load(p0, ws, bh, n + 8, td, te, lane);  scan_step(p1, acc, ws, lds, bh, n + 1, 1, td, te, lane); WG_BAR();
;             scanb_load(p1, ws, bh, n + 9, td, te, lane);  scan_step(p2, acc, ws, lds, bh, n + 2, 0, td, te, lane); WG_BAR();
;             scanb_load(p2, ws, bh, n + 10, td, te, lane); scan_step(p3, acc, ws, lds, bh, n + 3, 1, td, te, lane); WG_BAR();
;             scanb_load(p3, ws, bh, n + 11, td, te, lane); scan_step(p4, acc, ws, lds, bh, n + 4, 0, td, te, lane); WG_BAR();
;             scanb_load(p4, ws, bh, n + 12, td, te, lane); scan_step(p5, acc, ws, lds, bh, n + 5, 1, td, te, lane); WG_BAR();
;             scanb_load(p5, ws, bh, n + 13, td, te, lane); scan_step(p6, acc, ws, lds, bh, n + 6, 0, td, te, lane); WG_BAR();
;             scanb_load(p6, ws, bh, n + 14, td, te, lane); scan_step(p7, acc, ws, lds, bh, n + 7, 1, td, te, lane); WG_BAR();
;         }
;     } else {
;         ScanA s0, s1, s2, s3;
;         scana_load(s0, ws, bh, 0, td, lane); scana_load(s1, ws, bh, 1, td, lane); scana_load(s2, ws, bh, 2, td, lane);
;         scana_put(s0, lds, 0, td, lane); scana_put(s1, lds, 1, td, lane); scana_put(s2, lds, 2, td, lane);
;         scana_load(s3, ws, bh, 3, td, lane); scana_load(s0, ws, bh, 4, td, lane); scana_load(s1, ws, bh, 5, td, lane); scana_load(s2, ws, bh, 6, td, lane);
;         WG_BAR();
; #pragma unroll 1
;         for (int n = 0; n < NCH; n += 4) {
;             scana_put(s3, lds, n + 3, td, lane); scana_load(s3, ws, bh, n + 7, td, lane); WG_BAR();
.LBB0_1053:
	s_and_b64 vcc, exec, s[4:5]
	s_cbranch_vccz .LBB0_1069
	v_lshrrev_b32_e32 v0, 9, v206
	v_xor_b32_e32 v1, 7, v0
	v_lshl_add_u32 v0, v206, 2, 0
	v_mov_b32_e32 v2, 0
	v_cmp_lt_u32_e32 vcc, 4, v1
	v_cmp_lt_u32_e64 s[4:5], 3, v1
	ds_write2st64_b32 v0, v2, v2 offset1:8
	ds_write2st64_b32 v0, v2, v2 offset0:16 offset1:24
	s_and_saveexec_b64 s[6:7], s[4:5]
	ds_write_b32 v0, v2 offset:8192
	s_or_b64 exec, exec, s[6:7]
	s_and_saveexec_b64 s[4:5], vcc
	v_mov_b32_e32 v2, 0
	ds_write_b32 v0, v2 offset:10240
	s_or_b64 exec, exec, s[4:5]
	v_cmp_lt_u32_e32 vcc, 6, v1
	v_cmp_lt_u32_e64 s[4:5], 5, v1
	s_and_saveexec_b64 s[6:7], s[4:5]
	v_mov_b32_e32 v1, 0
	ds_write_b32 v0, v1 offset:12288
	s_or_b64 exec, exec, s[6:7]
	s_and_saveexec_b64 s[4:5], vcc
	v_mov_b32_e32 v1, 0
	ds_write_b32 v0, v1 offset:14336
	s_or_b64 exec, exec, s[4:5]
	s_mov_b64 s[4:5], -1
	s_cmpk_gt_u32 s70, 0xff
	v_lshlrev_b32_e32 v128, 4, v200
	s_cbranch_scc0 .LBB0_1066
	s_add_u32 s10, s92, 0x2c00000
	s_addc_u32 s11, s93, 0
	s_lshl_b32 s4, s2, 5
	s_and_b32 s4, s4, 0x80
	s_lshl_b32 s6, s2, 15
	s_lshl_b32 s5, s4, 17
	s_and_b32 s6, s6, 0x18000
	s_or_b32 s5, s5, s6
	s_add_u32 s5, s10, s5
	s_addc_u32 s7, s11, 0
	s_lshl_b32 s8, s70, 7
	s_and_b32 s12, s8, 0x6000
	s_add_u32 s8, s5, s12
	s_addc_u32 s9, s7, 0
	v_mov_b32_e32 v129, 0
	v_lshl_add_u64 v[56:57], s[8:9], 0, v[128:129]
	s_movk_i32 s7, 0x1000
	v_add_co_u32_e32 v0, vcc, s7, v56
	s_mov_b32 s5, 0x21000
	s_nop 0
	v_addc_co_u32_e32 v1, vcc, 0, v57, vcc
	v_add_co_u32_e32 v2, vcc, s5, v56
	s_mov_b32 s5, 0x41000
	s_nop 0
	v_addc_co_u32_e32 v3, vcc, 0, v57, vcc
	s_waitcnt lgkmcnt(2)
	s_mov_b64 s[8:9], 0x20000
	v_add_co_u32_e32 v6, vcc, s5, v56
	global_load_dwordx4 v[158:161], v[0:1], off offset:2048
	global_load_dwordx4 v[162:165], v[0:1], off offset:3072
	v_lshl_add_u64 v[0:1], v[56:57], 0, s[8:9]
	s_mov_b64 s[8:9], 0x40000
	v_addc_co_u32_e32 v7, vcc, 0, v57, vcc
	s_mov_b32 s5, 0x61000
	global_load_dwordx4 v[186:189], v[2:3], off offset:2048
	v_lshl_add_u64 v[4:5], v[56:57], 0, s[8:9]
	global_load_dwordx4 v[190:193], v[2:3], off offset:3072
	global_load_dwordx4 v[228:231], v[6:7], off offset:2048
	global_load_dwordx4 v[232:235], v[6:7], off offset:3072
	v_add_co_u32_e32 v0, vcc, s5, v56
	s_mov_b32 s5, 0x81000
	s_nop 0
	v_addc_co_u32_e32 v1, vcc, 0, v57, vcc
	v_add_co_u32_e32 v28, vcc, s5, v56
	s_mov_b64 s[8:9], 0x60000
	s_nop 0
	v_addc_co_u32_e32 v29, vcc, 0, v57, vcc
	s_mov_b32 s5, 0xa1000
	v_lshl_add_u64 v[4:5], v[56:57], 0, s[8:9]
	s_mov_b64 s[8:9], 0x80000
	v_add_co_u32_e32 v58, vcc, s5, v56
	v_lshl_add_u64 v[12:13], v[56:57], 0, s[8:9]
	s_mov_b64 s[8:9], 0xa0000
	v_addc_co_u32_e32 v59, vcc, 0, v57, vcc
	s_mov_b32 s5, 0xc1000
	v_lshl_add_u64 v[64:65], v[56:57], 0, s[8:9]
	s_mov_b64 s[8:9], 0xc0000
	v_add_co_u32_e32 v92, vcc, s5, v56
	v_lshl_add_u64 v[76:77], v[56:57], 0, s[8:9]
	s_nop 0
	v_addc_co_u32_e32 v93, vcc, 0, v57, vcc
	global_load_dwordx4 v[116:119], v[0:1], off offset:2048
	global_load_dwordx4 v[124:127], v[0:1], off offset:3072
	s_nop 0
	s_nop 0
	s_nop 0
	s_nop 0
	global_load_dwordx4 v[24:27], v[28:29], off offset:2048
	s_nop 0
	global_load_dwordx4 v[28:31], v[28:29], off offset:3072
	s_nop 0
	global_load_dwordx4 v[52:55], v[58:59], off offset:2048
	s_nop 0
	global_load_dwordx4 v[56:59], v[58:59], off offset:3072
	s_nop 0
	s_nop 0
	s_nop 0
	s_nop 0
	s_nop 0
	global_load_dwordx4 v[88:91], v[92:93], off offset:2048
	s_nop 0
	global_load_dwordx4 v[92:95], v[92:93], off offset:3072
	s_add_i32 s8, s12, 0
	s_add_i32 s9, s8, 0x14000
	v_add_u32_e32 v132, s8, v128
	v_add_u32_e32 v133, s9, v128
	s_add_i32 s8, s8, 0x1c000
	s_or_b32 s9, s4, 7
	s_add_u32 s10, s10, s12
	s_addc_u32 s11, s11, 0
	s_mov_b32 s5, 0
	v_lshl_add_u64 v[130:131], s[10:11], 0, v[128:129]
	s_or_b32 s10, s4, 8
	s_or_b32 s11, s4, 9
	s_or_b32 s12, s4, 10
	s_mov_b32 s13, -4
	s_waitcnt vmcnt(13)
	ds_write_b128 v132, v[158:161] offset:22528
	s_waitcnt vmcnt(12)
	ds_write_b128 v132, v[162:165] offset:23552
	s_waitcnt vmcnt(11)
	ds_write_b128 v132, v[186:189] offset:55296
	s_waitcnt vmcnt(10)
	ds_write_b128 v132, v[190:193] offset:56320
	s_waitcnt vmcnt(9)
	ds_write_b128 v133, v[228:231] offset:6144
	s_waitcnt vmcnt(8)
	ds_write_b128 v133, v[232:235] offset:7168
	s_waitcnt lgkmcnt(0)
	s_barrier
.LBB0_1064:
	s_add_i32 s13, s13, 4
	s_min_u32 s4, s13, 0x78
	s_add_i32 s4, s9, s4
	s_min_u32 s14, s13, 0x77
	s_lshl_b32 s4, s4, 17
	v_add_u32_e32 v129, s8, v128
	s_add_i32 s14, s10, s14
	s_or_b32 s4, s4, s6
	s_waitcnt vmcnt(7)
	ds_write_b128 v129, v[116:119] offset:6144
	s_waitcnt vmcnt(6)
	ds_write_b128 v129, v[124:127] offset:7168
	s_min_u32 s15, s13, 0x76
	s_lshl_b32 s14, s14, 17
	v_lshl_add_u64 v[108:109], v[130:131], 0, s[4:5]
	s_add_i32 s15, s11, s15
	s_or_b32 s4, s14, s6
	v_add_co_u32_e32 v124, vcc, s7, v108
	s_lshl_b32 s15, s15, 17
	s_nop 0
	v_addc_co_u32_e32 v125, vcc, 0, v109, vcc
	v_lshl_add_u64 v[134:135], v[130:131], 0, s[4:5]
	s_or_b32 s4, s15, s6
	global_load_dwordx4 v[116:119], v[124:125], off offset:2048
	s_nop 0
	global_load_dwordx4 v[124:127], v[124:125], off offset:3072
	s_waitcnt lgkmcnt(0)
	s_barrier
	s_waitcnt vmcnt(7)
	ds_write_b128 v132, v[24:27] offset:22528
	s_waitcnt vmcnt(6)
	ds_write_b128 v132, v[28:31] offset:23552
	v_add_co_u32_e32 v28, vcc, s7, v134
	v_lshl_add_u64 v[136:137], v[130:131], 0, s[4:5]
	s_nop 0
	v_addc_co_u32_e32 v29, vcc, 0, v135, vcc
	s_min_u32 s18, s13, 0x75
	global_load_dwordx4 v[24:27], v[28:29], off offset:2048
	s_nop 0
	global_load_dwordx4 v[28:31], v[28:29], off offset:3072
	s_waitcnt lgkmcnt(0)
	s_barrier
	s_waitcnt vmcnt(7)
	ds_write_b128 v132, v[52:55] offset:55296
	s_waitcnt vmcnt(6)
	ds_write_b128 v132, v[56:59] offset:56320
	v_add_co_u32_e32 v56, vcc, s7, v136
	s_add_i32 s18, s12, s18
	s_nop 0
	v_addc_co_u32_e32 v57, vcc, 0, v137, vcc
	s_lshl_b32 s18, s18, 17
	global_load_dwordx4 v[52:55], v[56:57], off offset:2048
	s_nop 0
	global_load_dwordx4 v[56:59], v[56:57], off offset:3072
	s_or_b32 s4, s18, s6
	v_lshl_add_u64 v[134:135], v[130:131], 0, s[4:5]
	s_waitcnt lgkmcnt(0)
	s_barrier
	s_waitcnt vmcnt(7)
	ds_write_b128 v133, v[88:91] offset:6144
	s_waitcnt vmcnt(6)
	ds_write_b128 v133, v[92:95] offset:7168
	v_add_co_u32_e32 v92, vcc, 0x1000, v134
	v_addc_co_u32_e32 v93, vcc, 0, v135, vcc
	global_load_dwordx4 v[88:91], v[92:93], off offset:2048
	s_nop 0
	global_load_dwordx4 v[92:95], v[92:93], off offset:3072
	s_waitcnt lgkmcnt(0)
	s_barrier
	s_cmpk_gt_u32 s13, 0x7b
	s_cbranch_scc0 .LBB0_1064
	s_mov_b64 s[4:5], 0
; #define WG_BAR() do { asm volatile("s_waitcnt lgkmcnt(0)" ::: "memory"); __builtin_amdgcn_s_barrier(); asm volatile("" ::: "memory"); } while (0)
; __device__ __forceinline__ int scan_item(int bh, int n) { if (n > NCH - 1) n = NCH - 1; return ((bh >> 2) * NCH + n) * 4 + (bh & 3); }
; __device__ __forceinline__ void scana_load(ScanA& p, const unsigned char* ws, int bh, int n, int td, int lane) {
;     const bf16* Ms = (const bf16*)(ws + WS_MS) + (size_t)scan_item(bh, n) * 16384 + td * 4096 + lane * 8;
; #pragma unroll
;     for (int q = 0; q < 8; ++q) p.a[q] = *(const bf16x8*)(Ms + 512 * q);
; __device__ __forceinline__ void dn_scan(const Args& a, LAS unsigned char* lds, int wg, int tid, int wave, int lane) {
;     ...
;     if (wave < 4) {
;         f32x16 acc = zero16();
;         ScanB p0, p1, p2, p3, p4, p5, p6, p7;
;         scanb_load(p0, ws, bh, 0, td, te, lane); scanb_load(p1, ws, bh, 1, td, te, lane); scanb_load(p2, ws, bh, 2, td, te, lane); scanb_load(p3, ws, bh, 3, td, te, lane);
;         scanb_load(p4, ws, bh, 4, td, te, lane); scanb_load(p5, ws, bh, 5, td, te, lane); scanb_load(p6, ws, bh, 6, td, te, lane);
;         WG_BAR();
.LBB0_1066:
	s_and_b64 vcc, exec, s[4:5]
	s_cbranch_vccz .LBB0_1069
	s_lshl_b32 s4, s2, 5
	s_and_b32 s12, s4, 0x80
	s_lshl_b32 s4, s12, 2
	s_and_b32 s13, s2, 3
	s_or_b32 s8, s4, s13
	s_add_u32 s4, s92, 0x1390000
	s_addc_u32 s5, s93, 0
	s_lshl_b32 s6, s8, 2
	s_add_u32 s9, s92, 0xcc00000
	s_waitcnt vmcnt(23)
	v_mov_b32_e32 v0, s6
	s_addc_u32 s10, s93, 0
	s_lshl_b32 s6, s8, 15
	s_add_u32 s6, s9, s6
	s_addc_u32 s7, s10, 0
	s_lshl_b32 s14, s2, 10
	s_lshl_b32 s11, s64, 11
	s_and_b32 s14, s14, 0x6000
	s_or_b32 s11, s11, s14
	s_add_u32 s6, s6, s11
	s_addc_u32 s7, s7, 0
	global_load_dwordx4 v[60:63], v128, s[6:7]
	global_load_dwordx4 v[56:59], v128, s[6:7] offset:1024
	s_or_b32 s6, s8, 4
	s_lshl_b32 s7, s6, 2
	s_lshl_b32 s6, s6, 15
	s_add_u32 s6, s9, s6
	v_mov_b32_e32 v1, s7
	s_addc_u32 s7, s10, 0
	s_add_u32 s6, s6, s11
	s_addc_u32 s7, s7, 0
	global_load_dwordx4 v[76:79], v128, s[6:7]
	global_load_dwordx4 v[68:71], v128, s[6:7] offset:1024
	s_or_b32 s6, s8, 8
	s_lshl_b32 s7, s6, 2
	s_lshl_b32 s6, s6, 15
	s_add_u32 s6, s9, s6
	v_mov_b32_e32 v2, s7
	s_addc_u32 s7, s10, 0
	s_add_u32 s6, s6, s11
	s_addc_u32 s7, s7, 0
	global_load_dwordx4 v[84:87], v128, s[6:7]
	global_load_dwordx4 v[80:83], v128, s[6:7] offset:1024
	s_or_b32 s6, s8, 12
	s_lshl_b32 s7, s6, 2
	s_lshl_b32 s6, s6, 15
	s_add_u32 s6, s9, s6
	v_mov_b32_e32 v3, s7
	s_addc_u32 s7, s10, 0
	s_add_u32 s6, s6, s11
	s_addc_u32 s7, s7, 0
	global_load_dwordx4 v[36:39], v128, s[6:7]
	global_load_dwordx4 v[32:35], v128, s[6:7] offset:1024
	s_or_b32 s6, s8, 16
	s_lshl_b32 s7, s6, 2
	s_lshl_b32 s6, s6, 15
	s_add_u32 s6, s9, s6
	s_waitcnt vmcnt(30)
	v_mov_b32_e32 v4, s7
	s_addc_u32 s7, s10, 0
	s_add_u32 s6, s6, s11
	s_addc_u32 s7, s7, 0
	global_load_dwordx4 v[44:47], v128, s[6:7]
	global_load_dwordx4 v[40:43], v128, s[6:7] offset:1024
	s_or_b32 s6, s8, 20
	s_lshl_b32 s7, s6, 2
	s_lshl_b32 s6, s6, 15
	s_add_u32 s6, s9, s6
	v_mov_b32_e32 v5, s7
	s_addc_u32 s7, s10, 0
	s_add_u32 s6, s6, s11
	s_addc_u32 s7, s7, 0
	global_load_dwordx4 v[52:55], v128, s[6:7]
	global_load_dwordx4 v[48:51], v128, s[6:7] offset:1024
	s_or_b32 s6, s8, 24
	s_lshl_b32 s7, s6, 2
	v_mov_b32_e32 v6, s7
	global_load_dword v126, v0, s[4:5]
	global_load_dword v124, v1, s[4:5]
	global_load_dword v122, v2, s[4:5]
	global_load_dword v114, v3, s[4:5]
	global_load_dword v116, v4, s[4:5]
	global_load_dword v118, v5, s[4:5]
	global_load_dword v120, v6, s[4:5]
	s_lshl_b32 s6, s6, 15
	s_add_u32 s6, s9, s6
	s_addc_u32 s7, s10, 0
	s_add_u32 s6, s6, s11
	s_addc_u32 s7, s7, 0
	global_load_dwordx4 v[72:75], v128, s[6:7]
	global_load_dwordx4 v[64:67], v128, s[6:7] offset:1024
	s_add_u32 s8, s9, s11
	s_addc_u32 s9, s10, 0
	s_lshl_b32 s6, s64, 13
	v_mov_b32_e32 v129, 0
	s_add_i32 s14, s6, 0
	s_mul_i32 s6, s64, 0xffffe800
	v_lshl_add_u64 v[96:97], s[8:9], 0, v[128:129]
	s_add_i32 s15, s14, s6
	s_mul_i32 s9, s64, 0x1800
	s_add_i32 s18, s15, s9
	s_bfe_u32 s9, s2, 0x10002
	s_lshl_b32 s8, s13, 15
	s_add_i32 s19, s18, s6
	s_lshl_b32 s6, s9, 24
	s_or_b32 s8, s6, s8
	s_mov_b32 s7, 0
	v_lshl_or_b32 v0, v200, 4, s11
	v_mov_b32_e32 v1, v129
	s_or_b32 s6, s8, 0xc0000
	v_lshl_add_u64 v[98:99], v[0:1], 0, s[6:7]
	s_or_b32 s6, s8, 0xa0000
	v_lshl_add_u64 v[100:101], v[0:1], 0, s[6:7]
	s_or_b32 s6, s8, 0x80000
	v_lshl_add_u64 v[102:103], v[0:1], 0, s[6:7]
	s_or_b32 s6, s8, 0x60000
	v_lshl_add_u64 v[104:105], v[0:1], 0, s[6:7]
	s_or_b32 s6, s8, 0x40000
	v_lshl_add_u64 v[106:107], v[0:1], 0, s[6:7]
	s_or_b32 s6, s8, 0x20000
	v_lshl_add_u64 v[108:109], v[0:1], 0, s[6:7]
	s_lshl_b32 s6, s9, 9
	s_or_b32 s6, s6, s13
	s_or_b32 s9, s6, 28
	s_waitcnt lgkmcnt(0)
	s_barrier
	s_lshl_b32 s6, s9, 2
	s_or_b32 s6, s6, 0x1390000
	s_lshl_b32 s10, s9, 15
	s_mov_b32 s11, s7
	s_mov_b32 s9, s7
	s_or_b32 s20, s12, 9
	s_add_i32 s21, s14, 0x14000
	s_or_b32 s22, s12, 10
	s_add_i32 s23, s14, 0x1c000
	s_or_b32 s24, s12, 11
	s_or_b32 s25, s12, 12
	s_or_b32 s26, s12, 13
	s_or_b32 s27, s12, 14
	v_lshl_add_u64 v[110:111], v[0:1], 0, s[10:11]
	v_lshl_add_u64 v[112:113], v[0:1], 0, s[8:9]
	s_mov_b32 s30, -8
	s_mov_b32 s28, 0xcc00000
	s_mov_b64 s[8:9], 0x100000
	s_mov_b64 s[10:11], s[6:7]
	v_mov_b32_e32 v0, 0
	v_mov_b32_e32 v2, 0
	v_mov_b32_e32 v3, v129
	v_mov_b32_e32 v4, 0
	v_mov_b32_e32 v5, v129
	v_mov_b32_e32 v6, 0
	v_mov_b32_e32 v7, v129
	s_waitcnt vmcnt(42)
	v_mov_b32_e32 v8, 0
	v_mov_b32_e32 v9, v129
	v_mov_b32_e32 v10, 0
	v_mov_b32_e32 v11, v129
	s_waitcnt vmcnt(41)
	v_mov_b32_e32 v12, 0
	v_mov_b32_e32 v13, v129
	v_mov_b32_e32 v14, 0
	v_mov_b32_e32 v15, v129
	s_bfe_u32 s98, s2, 0x10002
	s_lshl_b32 s98, s98, 24
	s_and_b32 s100, s2, 3
	s_lshl_b32 s100, s100, 15
	s_or_b32 s98, s98, s100
	s_lshl_b32 s100, s64, 13
	s_or_b32 s98, s98, s100
	s_add_u32 s98, s98, 0x2c00000
	s_add_u32 s100, s92, s98
	s_addc_u32 s101, s93, 0
	v_add_u32_e32 v147, 0x1000, v128
	global_load_dwordx4 v[148:151], v128, s[100:101]
	global_load_dwordx4 v[152:155], v128, s[100:101] offset:1024
	global_load_dwordx4 v[156:159], v128, s[100:101] offset:2048
	global_load_dwordx4 v[160:163], v128, s[100:101] offset:3072
	global_load_dwordx4 v[164:167], v147, s[100:101]
	global_load_dwordx4 v[168:171], v147, s[100:101] offset:1024
	v_add_u32_e32 v146, 0x20000, v128
	v_add_u32_e32 v147, 0x21000, v128
	global_load_dwordx4 v[172:175], v146, s[100:101]
	global_load_dwordx4 v[176:179], v146, s[100:101] offset:1024
	global_load_dwordx4 v[180:183], v146, s[100:101] offset:2048
	global_load_dwordx4 v[184:187], v146, s[100:101] offset:3072
	global_load_dwordx4 v[188:191], v147, s[100:101]
	global_load_dwordx4 v[192:195], v147, s[100:101] offset:1024
	v_add_u32_e32 v146, 0x40000, v128
	v_add_u32_e32 v147, 0x41000, v128
	global_load_dwordx4 v[196:199], v146, s[100:101]
	global_load_dwordx4 v[208:211], v146, s[100:101] offset:1024
	global_load_dwordx4 v[212:215], v146, s[100:101] offset:2048
	global_load_dwordx4 v[216:219], v146, s[100:101] offset:3072
	global_load_dwordx4 v[220:223], v147, s[100:101]
	global_load_dwordx4 v[224:227], v147, s[100:101] offset:1024
	v_add_u32_e32 v146, 0x60000, v128
	v_add_u32_e32 v147, 0x61000, v128
	global_load_dwordx4 v[228:231], v146, s[100:101]
	global_load_dwordx4 v[232:235], v146, s[100:101] offset:1024
	global_load_dwordx4 v[236:239], v146, s[100:101] offset:2048
	global_load_dwordx4 v[240:243], v146, s[100:101] offset:3072
	global_load_dwordx4 v[244:247], v147, s[100:101]
	global_load_dwordx4 v[248:251], v147, s[100:101] offset:1024
	s_waitcnt vmcnt(0)
; __device__ __forceinline__ void scan_step(const ScanB& p, f32x16& acc, unsigned char* ws, LAS unsigned char* lds, int bh, int n, int cur, int td, int te, int lane) {
;     const int item = scan_item(bh, n);
;     v4u b0 = p.bn[0], b1 = p.bn[1]; float egl = p.egl;
;     asm volatile("" : "+v"(egl)); asm volatile("" : "+v"(b0)); asm volatile("" : "+v"(b1));
;     f32x16 bv16; ans_unpack(b0, b1, bv16);
; #pragma unroll
;     for (int r = 0; r < 16; ++r) acc[r] = acc[r] * egl + bv16[r];
;     const LAS unsigned char* sb = lds + cur * 8192 + lane * 16;
;     const LAS unsigned char* sa = lds + SC_RING + (n & 3) * SC_SLOT + td * 8192 + lane * 16;
;     f32x16 acc2 = zero16();
; #pragma unroll
;     for (int q = 0; q < 8; q += 2) {
;         const bf16x8 a0 = *(const LAS bf16x8*)(sa + 1024 * q), bv0 = *(const LAS bf16x8*)(sb + 1024 * q);
;         const bf16x8 a1 = *(const LAS bf16x8*)(sa + 1024 * (q + 1)), bv1 = *(const LAS bf16x8*)(sb + 1024 * (q + 1));
;         acc = __builtin_amdgcn_mfma_f32_32x32x16_bf16(a0, bv0, acc, 0, 0, 0); acc2 = __builtin_amdgcn_mfma_f32_32x32x16_bf16(a1, bv1, acc2, 0, 0, 0); }
; #pragma unroll
;     for (int r = 0; r < 16; ++r) acc[r] += acc2[r];
;     v4u w0, w1; ans_pack(acc, w0, w1);
;     LAS unsigned char* sn = lds + (cur ^ 1) * 8192 + td * 2048 + lane * 16;
;     *(LAS v4u*)sn = w0; *(LAS v4u*)(sn + 1024) = w1;
;     bf16* So = (bf16*)(ws + WS_BS) + (size_t)item * 16384 + (te * 4 + td) * 1024 + lane * 8;
;     *(v4u*)So = w0; *(v4u*)(So + 512) = w1;
; __device__ __forceinline__ void dn_scan(const Args& a, LAS unsigned char* lds, int wg, int tid, int wave, int lane) {
;     ...
;             scanb_load(p7, ws, bh, n + 7, td, te, lane);  scan_step(p0, acc, ws, lds, bh, n, 0, td, te, lane); WG_BAR();
;             scanb_load(p0, ws, bh, n + 8, td, te, lane);  scan_step(p1, acc, ws, lds, bh, n + 1, 1, td, te, lane); WG_BAR();
;             scanb_load(p1, ws, bh, n + 9, td, te, lane);  scan_step(p2, acc, ws, lds, bh, n + 2, 0, td, te, lane); WG_BAR();
;             scanb_load(p2, ws, bh, n + 10, td, te, lane); scan_step(p3, acc, ws, lds, bh, n + 3, 1, td, te, lane); WG_BAR();
;             scanb_load(p3, ws, bh, n + 11, td, te, lane); scan_step(p4, acc, ws, lds, bh, n + 4, 0, td, te, lane); WG_BAR();
;             scanb_load(p4, ws, bh, n + 12, td, te, lane); scan_step(p5, acc, ws, lds, bh, n + 5, 1, td, te, lane); WG_BAR();
.LBB0_1068:
	v_lshl_add_u64 v[16:17], s[92:93], 0, v[110:111]
	s_add_i32 s29, s30, 8
	v_mov_b32_e32 v201, s29
	v_add_co_u32_e32 v130, vcc, s28, v16
	v_add_u32_e32 v123, s14, v128
	s_add_u32 s34, s92, s10
	v_addc_co_u32_e32 v131, vcc, 0, v17, vcc
	v_add_u32_e32 v115, 0, v128
	s_addc_u32 s35, s93, s11
	global_load_dwordx4 v[92:95], v[130:131], off
	global_load_dwordx4 v[88:91], v[130:131], off offset:1024
	global_load_dword v132, v129, s[34:35]
	ds_read_b128 v[24:27], v115
	ds_read_b128 v[28:31], v115 offset:1024
	v_lshlrev_b32_e32 v134, 16, v60
	v_and_b32_e32 v135, 0xffff0000, v60
	v_lshlrev_b32_e32 v60, 16, v61
	v_and_b32_e32 v61, 0xffff0000, v61
	v_lshlrev_b32_e32 v136, 16, v62
	v_and_b32_e32 v137, 0xffff0000, v62
	v_lshlrev_b32_e32 v62, 16, v63
	v_and_b32_e32 v63, 0xffff0000, v63
	v_lshlrev_b32_e32 v138, 16, v56
	v_and_b32_e32 v139, 0xffff0000, v56
	v_lshlrev_b32_e32 v56, 16, v57
	v_and_b32_e32 v57, 0xffff0000, v57
	v_lshlrev_b32_e32 v140, 16, v58
	v_and_b32_e32 v141, 0xffff0000, v58
	v_lshlrev_b32_e32 v58, 16, v59
	v_and_b32_e32 v59, 0xffff0000, v59
	v_pk_fma_f32 v[0:1], v[0:1], v[126:127], v[134:135] op_sel_hi:[1,0,1]
	v_pk_fma_f32 v[2:3], v[2:3], v[126:127], v[60:61] op_sel_hi:[1,0,1]
	v_pk_fma_f32 v[4:5], v[4:5], v[126:127], v[136:137] op_sel_hi:[1,0,1]
	v_pk_fma_f32 v[6:7], v[6:7], v[126:127], v[62:63] op_sel_hi:[1,0,1]
	v_pk_fma_f32 v[8:9], v[8:9], v[126:127], v[138:139] op_sel_hi:[1,0,1]
	v_pk_fma_f32 v[10:11], v[10:11], v[126:127], v[56:57] op_sel_hi:[1,0,1]
	v_pk_fma_f32 v[12:13], v[12:13], v[126:127], v[140:141] op_sel_hi:[1,0,1]
	v_pk_fma_f32 v[14:15], v[14:15], v[126:127], v[58:59] op_sel_hi:[1,0,1]
	ds_read_b128 v[60:63], v115 offset:2048
	ds_read_b128 v[138:141], v115 offset:3072
	v_add_u32_e32 v146, 4, v201
	v_min_u32_e32 v146, 0x7f, v146
	v_lshl_add_u32 v146, v146, 17, v128
	v_add_u32_e32 v147, 0x1000, v146
	s_waitcnt vmcnt(43)
	s_waitcnt lgkmcnt(3)
	v_mfma_f32_32x32x16_bf16 v[0:15], v[148:151], v[24:27], v[0:15]
	global_load_dwordx4 v[148:151], v146, s[100:101]
	s_add_i32 s6, s30, 16
	s_min_u32 s6, s6, 0x7f
	s_or_b32 s6, s6, s12
	s_lshl_b32 s6, s6, 2
	v_add_u32_e32 v117, s15, v128
	s_or_b32 s6, s6, s13
	s_lshl_b32 s30, s6, 2
	s_waitcnt vmcnt(43)
	s_waitcnt lgkmcnt(2)
	v_mfma_f32_32x32x16_bf16 v[16:31], v[152:155], v[28:31], 0
	global_load_dwordx4 v[152:155], v146, s[100:101] offset:1024
	v_add_u32_e32 v121, s18, v128
	s_lshl_b32 s6, s6, 15
	v_lshl_add_u64 v[142:143], v[96:97], 0, s[6:7]
	s_min_u32 s6, s29, 0x76
	s_add_i32 s6, s20, s6
	s_lshl_b32 s6, s6, 2
	v_add_u32_e32 v119, s19, v128
	s_waitcnt vmcnt(43)
	s_waitcnt lgkmcnt(1)
	v_mfma_f32_32x32x16_bf16 v[0:15], v[156:159], v[60:63], v[0:15]
	global_load_dwordx4 v[156:159], v146, s[100:101] offset:2048
	s_or_b32 s6, s6, s13
	v_lshl_add_u64 v[110:111], v[110:111], 0, s[8:9]
	s_waitcnt vmcnt(43)
	s_waitcnt lgkmcnt(0)
	v_mfma_f32_32x32x16_bf16 v[16:31], v[160:163], v[138:141], v[16:31]
	global_load_dwordx4 v[160:163], v146, s[100:101] offset:3072
	ds_read_b128 v[60:63], v115 offset:4096
	ds_read_b128 v[138:141], v115 offset:5120
	s_waitcnt vmcnt(43)
	s_waitcnt lgkmcnt(1)
	v_mfma_f32_32x32x16_bf16 v[0:15], v[164:167], v[60:63], v[0:15]
	global_load_dwordx4 v[164:167], v147, s[100:101]
	v_lshl_add_u64 v[56:57], s[92:93], 0, v[112:113]
	v_add_co_u32_e32 v126, vcc, s28, v56
	v_lshl_add_u64 v[112:113], v[112:113], 0, s[8:9]
	s_nop 0
	v_addc_co_u32_e32 v127, vcc, 0, v57, vcc
	s_waitcnt vmcnt(43)
	s_waitcnt lgkmcnt(0)
	v_mfma_f32_32x32x16_bf16 v[16:31], v[168:171], v[138:141], v[16:31]
	global_load_dwordx4 v[168:171], v147, s[100:101] offset:1024
	ds_read_b128 v[56:59], v123 offset:22528
	ds_read_b128 v[60:63], v115 offset:6144
	ds_read_b128 v[134:137], v123 offset:23552
	ds_read_b128 v[138:141], v115 offset:7168
	s_waitcnt lgkmcnt(2)
	v_mfma_f32_32x32x16_bf16 v[0:15], v[56:59], v[60:63], v[0:15]
	v_mov_b32_e32 v56, s30
	s_lshl_b32 s30, s6, 2
	s_lshl_b32 s6, s6, 15
	v_lshl_add_u64 v[144:145], v[96:97], 0, s[6:7]
	s_min_u32 s6, s29, 0x75
	s_add_i32 s6, s22, s6
	s_lshl_b32 s6, s6, 2
	s_waitcnt lgkmcnt(0)
	v_mfma_f32_32x32x16_bf16 v[16:31], v[134:137], v[138:141], v[16:31]
	s_or_b32 s6, s6, s13
	s_nop 10
	v_pk_add_f32 v[134:135], v[6:7], v[22:23]
	v_pk_add_f32 v[136:137], v[4:5], v[20:21]
	v_pk_add_f32 v[138:139], v[2:3], v[18:19]
	v_pk_add_f32 v[140:141], v[0:1], v[16:17]
	v_pk_add_f32 v[14:15], v[14:15], v[30:31]
	v_pk_add_f32 v[12:13], v[12:13], v[28:29]
	v_pk_add_f32 v[10:11], v[10:11], v[26:27]
	v_pk_add_f32 v[8:9], v[8:9], v[24:25]
	v_cvt_pk_bf16_f32 v0, v140, v141
	v_cvt_pk_bf16_f32 v1, v138, v139
	v_cvt_pk_bf16_f32 v2, v136, v137
	v_cvt_pk_bf16_f32 v3, v134, v135
	v_cvt_pk_bf16_f32 v4, v8, v9
	v_cvt_pk_bf16_f32 v5, v10, v11
	v_cvt_pk_bf16_f32 v6, v12, v13
	v_cvt_pk_bf16_f32 v7, v14, v15
	ds_write_b128 v117, v[0:3] offset:8192
	ds_write_b128 v117, v[4:7] offset:9216
	global_store_dwordx4 v[126:127], v[0:3], off
	global_store_dwordx4 v[126:127], v[4:7], off offset:1024
	s_waitcnt lgkmcnt(0)
	s_barrier
; __device__ __forceinline__ void scan_step(const ScanB& p, f32x16& acc, unsigned char* ws, LAS unsigned char* lds, int bh, int n, int cur, int td, int te, int lane) {
;     const int item = scan_item(bh, n);
;     v4u b0 = p.bn[0], b1 = p.bn[1]; float egl = p.egl;
;     asm volatile("" : "+v"(egl)); asm volatile("" : "+v"(b0)); asm volatile("" : "+v"(b1));
;     f32x16 bv16; ans_unpack(b0, b1, bv16);
; #pragma unroll
;     for (int r = 0; r < 16; ++r) acc[r] = acc[r] * egl + bv16[r];
;     const LAS unsigned char* sb = lds + cur * 8192 + lane * 16;
;     const LAS unsigned char* sa = lds + SC_RING + (n & 3) * SC_SLOT + td * 8192 + lane * 16;
;     f32x16 acc2 = zero16();
; #pragma unroll
;     for (int q = 0; q < 8; q += 2) {
;         const bf16x8 a0 = *(const LAS bf16x8*)(sa + 1024 * q), bv0 = *(const LAS bf16x8*)(sb + 1024 * q);
;         const bf16x8 a1 = *(const LAS bf16x8*)(sa + 1024 * (q + 1)), bv1 = *(const LAS bf16x8*)(sb + 1024 * (q + 1));
;         acc = __builtin_amdgcn_mfma_f32_32x32x16_bf16(a0, bv0, acc, 0, 0, 0); acc2 = __builtin_amdgcn_mfma_f32_32x32x16_bf16(a1, bv1, acc2, 0, 0, 0); }
; #pragma unroll
;     for (int r = 0; r < 16; ++r) acc[r] += acc2[r];
;     v4u w0, w1; ans_pack(acc, w0, w1);
;     LAS unsigned char* sn = lds + (cur ^ 1) * 8192 + td * 2048 + lane * 16;
;     *(LAS v4u*)sn = w0; *(LAS v4u*)(sn + 1024) = w1;
;     bf16* So = (bf16*)(ws + WS_BS) + (size_t)item * 16384 + (te * 4 + td) * 1024 + lane * 8;
;     *(v4u*)So = w0; *(v4u*)(So + 512) = w1;
; __device__ __forceinline__ void dn_scan(const Args& a, LAS unsigned char* lds, int wg, int tid, int wave, int lane) {
;     ...
;             scanb_load(p7, ws, bh, n + 7, td, te, lane);  scan_step(p0, acc, ws, lds, bh, n, 0, td, te, lane); WG_BAR();
;             scanb_load(p0, ws, bh, n + 8, td, te, lane);  scan_step(p1, acc, ws, lds, bh, n + 1, 1, td, te, lane); WG_BAR();
;             scanb_load(p1, ws, bh, n + 9, td, te, lane);  scan_step(p2, acc, ws, lds, bh, n + 2, 0, td, te, lane); WG_BAR();
;             scanb_load(p2, ws, bh, n + 10, td, te, lane); scan_step(p3, acc, ws, lds, bh, n + 3, 1, td, te, lane); WG_BAR();
;             scanb_load(p3, ws, bh, n + 11, td, te, lane); scan_step(p4, acc, ws, lds, bh, n + 4, 0, td, te, lane); WG_BAR();
;             scanb_load(p4, ws, bh, n + 12, td, te, lane); scan_step(p5, acc, ws, lds, bh, n + 5, 1, td, te, lane); WG_BAR();
	global_load_dword v126, v56, s[4:5]
	global_load_dwordx4 v[60:63], v[142:143], off
	s_nop 0
	global_load_dwordx4 v[56:59], v[142:143], off offset:1024
	ds_read_b128 v[24:27], v115 offset:8192
	ds_read_b128 v[28:31], v115 offset:9216
	v_lshlrev_b32_e32 v0, 16, v76
	v_and_b32_e32 v1, 0xffff0000, v76
	v_lshlrev_b32_e32 v2, 16, v77
	v_and_b32_e32 v3, 0xffff0000, v77
	v_lshlrev_b32_e32 v4, 16, v78
	v_and_b32_e32 v5, 0xffff0000, v78
	v_lshlrev_b32_e32 v6, 16, v79
	v_and_b32_e32 v7, 0xffff0000, v79
	v_lshlrev_b32_e32 v76, 16, v68
	v_and_b32_e32 v77, 0xffff0000, v68
	v_lshlrev_b32_e32 v68, 16, v69
	v_and_b32_e32 v69, 0xffff0000, v69
	v_lshlrev_b32_e32 v78, 16, v70
	v_and_b32_e32 v79, 0xffff0000, v70
	v_lshlrev_b32_e32 v70, 16, v71
	v_and_b32_e32 v71, 0xffff0000, v71
	v_pk_fma_f32 v[0:1], v[140:141], v[124:125], v[0:1] op_sel_hi:[1,0,1]
	v_pk_fma_f32 v[2:3], v[138:139], v[124:125], v[2:3] op_sel_hi:[1,0,1]
	v_pk_fma_f32 v[4:5], v[136:137], v[124:125], v[4:5] op_sel_hi:[1,0,1]
	v_pk_fma_f32 v[6:7], v[134:135], v[124:125], v[6:7] op_sel_hi:[1,0,1]
	v_pk_fma_f32 v[8:9], v[8:9], v[124:125], v[76:77] op_sel_hi:[1,0,1]
	v_pk_fma_f32 v[10:11], v[10:11], v[124:125], v[68:69] op_sel_hi:[1,0,1]
	v_pk_fma_f32 v[12:13], v[12:13], v[124:125], v[78:79] op_sel_hi:[1,0,1]
	v_pk_fma_f32 v[14:15], v[14:15], v[124:125], v[70:71] op_sel_hi:[1,0,1]
	ds_read_b128 v[76:79], v115 offset:10240
	ds_read_b128 v[138:141], v115 offset:11264
	v_add_u32_e32 v146, 5, v201
	v_min_u32_e32 v146, 0x7f, v146
	v_lshl_add_u32 v146, v146, 17, v128
	v_add_u32_e32 v147, 0x1000, v146
	s_waitcnt vmcnt(43)
	s_waitcnt lgkmcnt(3)
	v_mfma_f32_32x32x16_bf16 v[0:15], v[172:175], v[24:27], v[0:15]
	global_load_dwordx4 v[172:175], v146, s[100:101]
	v_add_u32_e32 v125, s21, v128
	v_add_u32_e32 v127, s23, v128
	s_waitcnt vmcnt(43)
	s_waitcnt lgkmcnt(2)
	v_mfma_f32_32x32x16_bf16 v[16:31], v[176:179], v[28:31], 0
	global_load_dwordx4 v[176:179], v146, s[100:101] offset:1024
	s_waitcnt vmcnt(43)
	s_waitcnt lgkmcnt(1)
	v_mfma_f32_32x32x16_bf16 v[0:15], v[180:183], v[76:79], v[0:15]
	global_load_dwordx4 v[180:183], v146, s[100:101] offset:2048
	s_waitcnt vmcnt(43)
	s_waitcnt lgkmcnt(0)
	v_mfma_f32_32x32x16_bf16 v[16:31], v[184:187], v[138:141], v[16:31]
	global_load_dwordx4 v[184:187], v146, s[100:101] offset:3072
	ds_read_b128 v[76:79], v115 offset:12288
	ds_read_b128 v[138:141], v115 offset:13312
	s_waitcnt vmcnt(43)
	s_waitcnt lgkmcnt(1)
	v_mfma_f32_32x32x16_bf16 v[0:15], v[188:191], v[76:79], v[0:15]
	global_load_dwordx4 v[188:191], v147, s[100:101]
	v_lshl_add_u64 v[68:69], s[92:93], 0, v[108:109]
	v_add_co_u32_e32 v142, vcc, s28, v68
	v_lshl_add_u64 v[108:109], v[108:109], 0, s[8:9]
	s_nop 0
	v_addc_co_u32_e32 v143, vcc, 0, v69, vcc
	s_waitcnt vmcnt(43)
	s_waitcnt lgkmcnt(0)
	v_mfma_f32_32x32x16_bf16 v[16:31], v[192:195], v[138:141], v[16:31]
	global_load_dwordx4 v[192:195], v147, s[100:101] offset:1024
	ds_read_b128 v[68:71], v121 offset:55296
	ds_read_b128 v[76:79], v115 offset:14336
	ds_read_b128 v[134:137], v121 offset:56320
	ds_read_b128 v[138:141], v115 offset:15360
	s_waitcnt lgkmcnt(2)
	v_mfma_f32_32x32x16_bf16 v[0:15], v[68:71], v[76:79], v[0:15]
	v_mov_b32_e32 v68, s30
	s_lshl_b32 s30, s6, 2
	s_lshl_b32 s6, s6, 15
	s_waitcnt lgkmcnt(0)
	v_mfma_f32_32x32x16_bf16 v[16:31], v[134:137], v[138:141], v[16:31]
	s_nop 11
	v_pk_add_f32 v[134:135], v[6:7], v[22:23]
	v_pk_add_f32 v[136:137], v[4:5], v[20:21]
	v_pk_add_f32 v[138:139], v[2:3], v[18:19]
	v_pk_add_f32 v[140:141], v[0:1], v[16:17]
	v_pk_add_f32 v[14:15], v[14:15], v[30:31]
	v_pk_add_f32 v[12:13], v[12:13], v[28:29]
	v_pk_add_f32 v[10:11], v[10:11], v[26:27]
	v_pk_add_f32 v[8:9], v[8:9], v[24:25]
	v_cvt_pk_bf16_f32 v0, v140, v141
	v_cvt_pk_bf16_f32 v1, v138, v139
	v_cvt_pk_bf16_f32 v2, v136, v137
	v_cvt_pk_bf16_f32 v3, v134, v135
	v_cvt_pk_bf16_f32 v4, v8, v9
	v_cvt_pk_bf16_f32 v5, v10, v11
	v_cvt_pk_bf16_f32 v6, v12, v13
	v_cvt_pk_bf16_f32 v7, v14, v15
	ds_write_b128 v119, v[0:3]
	ds_write_b128 v119, v[4:7] offset:1024
	global_store_dwordx4 v[142:143], v[0:3], off
	global_store_dwordx4 v[142:143], v[4:7], off offset:1024
	s_waitcnt lgkmcnt(0)
	s_barrier
	global_load_dword v124, v68, s[4:5]
	global_load_dwordx4 v[76:79], v[144:145], off
	s_nop 0
	global_load_dwordx4 v[68:71], v[144:145], off offset:1024
	ds_read_b128 v[24:27], v115
	ds_read_b128 v[28:31], v115 offset:1024
	v_lshlrev_b32_e32 v0, 16, v84
	v_and_b32_e32 v1, 0xffff0000, v84
	v_lshlrev_b32_e32 v2, 16, v85
	v_and_b32_e32 v3, 0xffff0000, v85
	v_lshlrev_b32_e32 v4, 16, v86
	v_and_b32_e32 v5, 0xffff0000, v86
	v_lshlrev_b32_e32 v6, 16, v87
	v_and_b32_e32 v7, 0xffff0000, v87
	v_lshlrev_b32_e32 v84, 16, v80
	v_and_b32_e32 v85, 0xffff0000, v80
	v_lshlrev_b32_e32 v80, 16, v81
	v_and_b32_e32 v81, 0xffff0000, v81
	v_lshlrev_b32_e32 v86, 16, v82
	v_and_b32_e32 v87, 0xffff0000, v82
	v_lshlrev_b32_e32 v82, 16, v83
	v_and_b32_e32 v83, 0xffff0000, v83
	v_pk_fma_f32 v[0:1], v[140:141], v[122:123], v[0:1] op_sel_hi:[1,0,1]
	v_pk_fma_f32 v[2:3], v[138:139], v[122:123], v[2:3] op_sel_hi:[1,0,1]
	v_pk_fma_f32 v[4:5], v[136:137], v[122:123], v[4:5] op_sel_hi:[1,0,1]
	v_pk_fma_f32 v[6:7], v[134:135], v[122:123], v[6:7] op_sel_hi:[1,0,1]
	v_pk_fma_f32 v[8:9], v[8:9], v[122:123], v[84:85] op_sel_hi:[1,0,1]
	v_pk_fma_f32 v[10:11], v[10:11], v[122:123], v[80:81] op_sel_hi:[1,0,1]
	v_pk_fma_f32 v[12:13], v[12:13], v[122:123], v[86:87] op_sel_hi:[1,0,1]
	v_pk_fma_f32 v[14:15], v[14:15], v[122:123], v[82:83] op_sel_hi:[1,0,1]
	ds_read_b128 v[84:87], v115 offset:2048
	ds_read_b128 v[138:141], v115 offset:3072
	v_add_u32_e32 v146, 6, v201
	v_min_u32_e32 v146, 0x7f, v146
	v_lshl_add_u32 v146, v146, 17, v128
	v_add_u32_e32 v147, 0x1000, v146
	s_waitcnt vmcnt(43)
; __device__ __forceinline__ void scan_step(const ScanB& p, f32x16& acc, unsigned char* ws, LAS unsigned char* lds, int bh, int n, int cur, int td, int te, int lane) {
;     const int item = scan_item(bh, n);
;     v4u b0 = p.bn[0], b1 = p.bn[1]; float egl = p.egl;
;     asm volatile("" : "+v"(egl)); asm volatile("" : "+v"(b0)); asm volatile("" : "+v"(b1));
;     f32x16 bv16; ans_unpack(b0, b1, bv16);
; #pragma unroll
;     for (int r = 0; r < 16; ++r) acc[r] = acc[r] * egl + bv16[r];
;     const LAS unsigned char* sb = lds + cur * 8192 + lane * 16;
;     const LAS unsigned char* sa = lds + SC_RING + (n & 3) * SC_SLOT + td * 8192 + lane * 16;
;     f32x16 acc2 = zero16();
; #pragma unroll
;     for (int q = 0; q < 8; q += 2) {
;         const bf16x8 a0 = *(const LAS bf16x8*)(sa + 1024 * q), bv0 = *(const LAS bf16x8*)(sb + 1024 * q);
;         const bf16x8 a1 = *(const LAS bf16x8*)(sa + 1024 * (q + 1)), bv1 = *(const LAS bf16x8*)(sb + 1024 * (q + 1));
;         acc = __builtin_amdgcn_mfma_f32_32x32x16_bf16(a0, bv0, acc, 0, 0, 0); acc2 = __builtin_amdgcn_mfma_f32_32x32x16_bf16(a1, bv1, acc2, 0, 0, 0); }
; #pragma unroll
;     for (int r = 0; r < 16; ++r) acc[r] += acc2[r];
;     v4u w0, w1; ans_pack(acc, w0, w1);
;     LAS unsigned char* sn = lds + (cur ^ 1) * 8192 + td * 2048 + lane * 16;
;     *(LAS v4u*)sn = w0; *(LAS v4u*)(sn + 1024) = w1;
;     bf16* So = (bf16*)(ws + WS_BS) + (size_t)item * 16384 + (te * 4 + td) * 1024 + lane * 8;
;     *(v4u*)So = w0; *(v4u*)(So + 512) = w1;
; __device__ __forceinline__ void dn_scan(const Args& a, LAS unsigned char* lds, int wg, int tid, int wave, int lane) {
;     ...
;             scanb_load(p7, ws, bh, n + 7, td, te, lane);  scan_step(p0, acc, ws, lds, bh, n, 0, td, te, lane); WG_BAR();
;             scanb_load(p0, ws, bh, n + 8, td, te, lane);  scan_step(p1, acc, ws, lds, bh, n + 1, 1, td, te, lane); WG_BAR();
;             scanb_load(p1, ws, bh, n + 9, td, te, lane);  scan_step(p2, acc, ws, lds, bh, n + 2, 0, td, te, lane); WG_BAR();
;             scanb_load(p2, ws, bh, n + 10, td, te, lane); scan_step(p3, acc, ws, lds, bh, n + 3, 1, td, te, lane); WG_BAR();
;             scanb_load(p3, ws, bh, n + 11, td, te, lane); scan_step(p4, acc, ws, lds, bh, n + 4, 0, td, te, lane); WG_BAR();
;             scanb_load(p4, ws, bh, n + 12, td, te, lane); scan_step(p5, acc, ws, lds, bh, n + 5, 1, td, te, lane); WG_BAR();
	s_waitcnt lgkmcnt(3)
	v_mfma_f32_32x32x16_bf16 v[0:15], v[196:199], v[24:27], v[0:15]
	global_load_dwordx4 v[196:199], v146, s[100:101]
	v_lshl_add_u64 v[144:145], v[96:97], 0, s[6:7]
	s_min_u32 s6, s29, 0x74
	s_add_i32 s6, s24, s6
	s_lshl_b32 s6, s6, 2
	s_or_b32 s6, s6, s13
	s_waitcnt vmcnt(43)
	s_waitcnt lgkmcnt(2)
	v_mfma_f32_32x32x16_bf16 v[16:31], v[208:211], v[28:31], 0
	global_load_dwordx4 v[208:211], v146, s[100:101] offset:1024
	s_waitcnt vmcnt(43)
	s_waitcnt lgkmcnt(1)
	v_mfma_f32_32x32x16_bf16 v[0:15], v[212:215], v[84:87], v[0:15]
	global_load_dwordx4 v[212:215], v146, s[100:101] offset:2048
	s_waitcnt vmcnt(43)
	s_waitcnt lgkmcnt(0)
	v_mfma_f32_32x32x16_bf16 v[16:31], v[216:219], v[138:141], v[16:31]
	global_load_dwordx4 v[216:219], v146, s[100:101] offset:3072
	ds_read_b128 v[84:87], v115 offset:4096
	ds_read_b128 v[138:141], v115 offset:5120
	s_waitcnt vmcnt(43)
	s_waitcnt lgkmcnt(1)
	v_mfma_f32_32x32x16_bf16 v[0:15], v[220:223], v[84:87], v[0:15]
	global_load_dwordx4 v[220:223], v147, s[100:101]
	v_lshl_add_u64 v[80:81], s[92:93], 0, v[106:107]
	v_add_co_u32_e32 v142, vcc, s28, v80
	v_lshl_add_u64 v[106:107], v[106:107], 0, s[8:9]
	s_nop 0
	v_addc_co_u32_e32 v143, vcc, 0, v81, vcc
	s_waitcnt vmcnt(43)
	s_waitcnt lgkmcnt(0)
	v_mfma_f32_32x32x16_bf16 v[16:31], v[224:227], v[138:141], v[16:31]
	global_load_dwordx4 v[224:227], v147, s[100:101] offset:1024
	ds_read_b128 v[80:83], v125 offset:6144
	ds_read_b128 v[84:87], v115 offset:6144
	ds_read_b128 v[134:137], v125 offset:7168
	ds_read_b128 v[138:141], v115 offset:7168
	s_waitcnt lgkmcnt(2)
	v_mfma_f32_32x32x16_bf16 v[0:15], v[80:83], v[84:87], v[0:15]
	v_mov_b32_e32 v80, s30
	s_lshl_b32 s30, s6, 2
	s_lshl_b32 s6, s6, 15
	s_waitcnt lgkmcnt(0)
	v_mfma_f32_32x32x16_bf16 v[16:31], v[134:137], v[138:141], v[16:31]
	s_nop 11
	v_pk_add_f32 v[134:135], v[6:7], v[22:23]
	v_pk_add_f32 v[136:137], v[4:5], v[20:21]
	v_pk_add_f32 v[138:139], v[2:3], v[18:19]
	v_pk_add_f32 v[140:141], v[0:1], v[16:17]
	v_pk_add_f32 v[14:15], v[14:15], v[30:31]
	v_pk_add_f32 v[12:13], v[12:13], v[28:29]
	v_pk_add_f32 v[10:11], v[10:11], v[26:27]
	v_pk_add_f32 v[8:9], v[8:9], v[24:25]
	v_cvt_pk_bf16_f32 v0, v140, v141
	v_cvt_pk_bf16_f32 v1, v138, v139
	v_cvt_pk_bf16_f32 v2, v136, v137
	v_cvt_pk_bf16_f32 v3, v134, v135
	v_cvt_pk_bf16_f32 v4, v8, v9
	v_cvt_pk_bf16_f32 v5, v10, v11
	v_cvt_pk_bf16_f32 v6, v12, v13
	v_cvt_pk_bf16_f32 v7, v14, v15
	ds_write_b128 v117, v[0:3] offset:8192
	ds_write_b128 v117, v[4:7] offset:9216
	global_store_dwordx4 v[142:143], v[0:3], off
	global_store_dwordx4 v[142:143], v[4:7], off offset:1024
	s_waitcnt lgkmcnt(0)
	s_barrier
	global_load_dword v122, v80, s[4:5]
	global_load_dwordx4 v[84:87], v[144:145], off
	s_nop 0
	global_load_dwordx4 v[80:83], v[144:145], off offset:1024
	ds_read_b128 v[24:27], v115 offset:8192
	ds_read_b128 v[28:31], v115 offset:9216
	v_lshlrev_b32_e32 v0, 16, v36
	v_and_b32_e32 v1, 0xffff0000, v36
	v_lshlrev_b32_e32 v2, 16, v37
	v_and_b32_e32 v3, 0xffff0000, v37
	v_lshlrev_b32_e32 v4, 16, v38
	v_and_b32_e32 v5, 0xffff0000, v38
	v_lshlrev_b32_e32 v6, 16, v39
	v_and_b32_e32 v7, 0xffff0000, v39
	v_lshlrev_b32_e32 v36, 16, v32
	v_and_b32_e32 v37, 0xffff0000, v32
	v_lshlrev_b32_e32 v32, 16, v33
	v_and_b32_e32 v33, 0xffff0000, v33
	v_lshlrev_b32_e32 v38, 16, v34
	v_and_b32_e32 v39, 0xffff0000, v34
	v_lshlrev_b32_e32 v34, 16, v35
	v_and_b32_e32 v35, 0xffff0000, v35
	v_pk_fma_f32 v[0:1], v[140:141], v[114:115], v[0:1] op_sel_hi:[1,0,1]
	v_pk_fma_f32 v[2:3], v[138:139], v[114:115], v[2:3] op_sel_hi:[1,0,1]
	v_pk_fma_f32 v[4:5], v[136:137], v[114:115], v[4:5] op_sel_hi:[1,0,1]
	v_pk_fma_f32 v[6:7], v[134:135], v[114:115], v[6:7] op_sel_hi:[1,0,1]
	v_pk_fma_f32 v[8:9], v[8:9], v[114:115], v[36:37] op_sel_hi:[1,0,1]
	v_pk_fma_f32 v[10:11], v[10:11], v[114:115], v[32:33] op_sel_hi:[1,0,1]
	v_pk_fma_f32 v[12:13], v[12:13], v[114:115], v[38:39] op_sel_hi:[1,0,1]
	v_pk_fma_f32 v[14:15], v[14:15], v[114:115], v[34:35] op_sel_hi:[1,0,1]
	ds_read_b128 v[36:39], v115 offset:10240
	ds_read_b128 v[138:141], v115 offset:11264
	v_add_u32_e32 v146, 7, v201
	v_min_u32_e32 v146, 0x7f, v146
	v_lshl_add_u32 v146, v146, 17, v128
	v_add_u32_e32 v147, 0x1000, v146
	s_waitcnt vmcnt(43)
	s_waitcnt lgkmcnt(3)
	v_mfma_f32_32x32x16_bf16 v[0:15], v[228:231], v[24:27], v[0:15]
	global_load_dwordx4 v[228:231], v146, s[100:101]
	v_lshl_add_u64 v[144:145], v[96:97], 0, s[6:7]
	s_min_u32 s6, s29, 0x73
	s_add_i32 s6, s25, s6
	s_lshl_b32 s6, s6, 2
	s_or_b32 s6, s6, s13
	s_waitcnt vmcnt(43)
	s_waitcnt lgkmcnt(2)
	v_mfma_f32_32x32x16_bf16 v[16:31], v[232:235], v[28:31], 0
	global_load_dwordx4 v[232:235], v146, s[100:101] offset:1024
	s_waitcnt vmcnt(43)
	s_waitcnt lgkmcnt(1)
	v_mfma_f32_32x32x16_bf16 v[0:15], v[236:239], v[36:39], v[0:15]
	global_load_dwordx4 v[236:239], v146, s[100:101] offset:2048
	s_waitcnt vmcnt(43)
	s_waitcnt lgkmcnt(0)
	v_mfma_f32_32x32x16_bf16 v[16:31], v[240:243], v[138:141], v[16:31]
	global_load_dwordx4 v[240:243], v146, s[100:101] offset:3072
	ds_read_b128 v[36:39], v115 offset:12288
	ds_read_b128 v[138:141], v115 offset:13312
	s_waitcnt vmcnt(43)
	s_waitcnt lgkmcnt(1)
	v_mfma_f32_32x32x16_bf16 v[0:15], v[244:247], v[36:39], v[0:15]
	global_load_dwordx4 v[244:247], v147, s[100:101]
	v_lshl_add_u64 v[32:33], s[92:93], 0, v[104:105]
	v_add_co_u32_e32 v142, vcc, s28, v32
	v_lshl_add_u64 v[104:105], v[104:105], 0, s[8:9]
	s_nop 0
	v_addc_co_u32_e32 v143, vcc, 0, v33, vcc
	s_waitcnt vmcnt(43)
	s_waitcnt lgkmcnt(0)
	v_mfma_f32_32x32x16_bf16 v[16:31], v[248:251], v[138:141], v[16:31]
	global_load_dwordx4 v[248:251], v147, s[100:101] offset:1024
	ds_read_b128 v[32:35], v127 offset:6144
	ds_read_b128 v[36:39], v115 offset:14336
	ds_read_b128 v[134:137], v127 offset:7168
	ds_read_b128 v[138:141], v115 offset:15360
	s_waitcnt lgkmcnt(2)
	v_mfma_f32_32x32x16_bf16 v[0:15], v[32:35], v[36:39], v[0:15]
	v_mov_b32_e32 v32, s30
	s_lshl_b32 s30, s6, 2
	s_lshl_b32 s6, s6, 15
	s_waitcnt lgkmcnt(0)
	v_mfma_f32_32x32x16_bf16 v[16:31], v[134:137], v[138:141], v[16:31]
	s_nop 11
	v_pk_add_f32 v[134:135], v[6:7], v[22:23]
	v_pk_add_f32 v[136:137], v[4:5], v[20:21]
	v_pk_add_f32 v[138:139], v[2:3], v[18:19]
	v_pk_add_f32 v[140:141], v[0:1], v[16:17]
	v_pk_add_f32 v[14:15], v[14:15], v[30:31]
	v_pk_add_f32 v[12:13], v[12:13], v[28:29]
	v_pk_add_f32 v[10:11], v[10:11], v[26:27]
	v_pk_add_f32 v[8:9], v[8:9], v[24:25]
	v_cvt_pk_bf16_f32 v0, v140, v141
	v_cvt_pk_bf16_f32 v1, v138, v139
	v_cvt_pk_bf16_f32 v2, v136, v137
	v_cvt_pk_bf16_f32 v3, v134, v135
	v_cvt_pk_bf16_f32 v4, v8, v9
	v_cvt_pk_bf16_f32 v5, v10, v11
	v_cvt_pk_bf16_f32 v6, v12, v13
	v_cvt_pk_bf16_f32 v7, v14, v15
	ds_write_b128 v119, v[0:3]
	ds_write_b128 v119, v[4:7] offset:1024
	global_store_dwordx4 v[142:143], v[0:3], off
	global_store_dwordx4 v[142:143], v[4:7], off offset:1024
	s_waitcnt lgkmcnt(0)
	s_barrier
; __device__ __forceinline__ void scan_step(const ScanB& p, f32x16& acc, unsigned char* ws, LAS unsigned char* lds, int bh, int n, int cur, int td, int te, int lane) {
;     const int item = scan_item(bh, n);
;     v4u b0 = p.bn[0], b1 = p.bn[1]; float egl = p.egl;
;     asm volatile("" : "+v"(egl)); asm volatile("" : "+v"(b0)); asm volatile("" : "+v"(b1));
;     f32x16 bv16; ans_unpack(b0, b1, bv16);
; #pragma unroll
;     for (int r = 0; r < 16; ++r) acc[r] = acc[r] * egl + bv16[r];
;     const LAS unsigned char* sb = lds + cur * 8192 + lane * 16;
;     const LAS unsigned char* sa = lds + SC_RING + (n & 3) * SC_SLOT + td * 8192 + lane * 16;
;     f32x16 acc2 = zero16();
; #pragma unroll
;     for (int q = 0; q < 8; q += 2) {
;         const bf16x8 a0 = *(const LAS bf16x8*)(sa + 1024 * q), bv0 = *(const LAS bf16x8*)(sb + 1024 * q);
;         const bf16x8 a1 = *(const LAS bf16x8*)(sa + 1024 * (q + 1)), bv1 = *(const LAS bf16x8*)(sb + 1024 * (q + 1));
;         acc = __builtin_amdgcn_mfma_f32_32x32x16_bf16(a0, bv0, acc, 0, 0, 0); acc2 = __builtin_amdgcn_mfma_f32_32x32x16_bf16(a1, bv1, acc2, 0, 0, 0); }
; #pragma unroll
;     for (int r = 0; r < 16; ++r) acc[r] += acc2[r];
;     v4u w0, w1; ans_pack(acc, w0, w1);
;     LAS unsigned char* sn = lds + (cur ^ 1) * 8192 + td * 2048 + lane * 16;
;     *(LAS v4u*)sn = w0; *(LAS v4u*)(sn + 1024) = w1;
;     bf16* So = (bf16*)(ws + WS_BS) + (size_t)item * 16384 + (te * 4 + td) * 1024 + lane * 8;
;     *(v4u*)So = w0; *(v4u*)(So + 512) = w1;
; __device__ __forceinline__ void dn_scan(const Args& a, LAS unsigned char* lds, int wg, int tid, int wave, int lane) {
;     ...
;             scanb_load(p7, ws, bh, n + 7, td, te, lane);  scan_step(p0, acc, ws, lds, bh, n, 0, td, te, lane); WG_BAR();
;             scanb_load(p0, ws, bh, n + 8, td, te, lane);  scan_step(p1, acc, ws, lds, bh, n + 1, 1, td, te, lane); WG_BAR();
;             scanb_load(p1, ws, bh, n + 9, td, te, lane);  scan_step(p2, acc, ws, lds, bh, n + 2, 0, td, te, lane); WG_BAR();
;             scanb_load(p2, ws, bh, n + 10, td, te, lane); scan_step(p3, acc, ws, lds, bh, n + 3, 1, td, te, lane); WG_BAR();
;             scanb_load(p3, ws, bh, n + 11, td, te, lane); scan_step(p4, acc, ws, lds, bh, n + 4, 0, td, te, lane); WG_BAR();
;             scanb_load(p4, ws, bh, n + 12, td, te, lane); scan_step(p5, acc, ws, lds, bh, n + 5, 1, td, te, lane); WG_BAR();
	global_load_dword v114, v32, s[4:5]
	global_load_dwordx4 v[36:39], v[144:145], off
	s_nop 0
	global_load_dwordx4 v[32:35], v[144:145], off offset:1024
	ds_read_b128 v[24:27], v115
	ds_read_b128 v[28:31], v115 offset:1024
	v_lshlrev_b32_e32 v0, 16, v44
	v_and_b32_e32 v1, 0xffff0000, v44
	v_lshlrev_b32_e32 v2, 16, v45
	v_and_b32_e32 v3, 0xffff0000, v45
	v_lshlrev_b32_e32 v4, 16, v46
	v_and_b32_e32 v5, 0xffff0000, v46
	v_lshlrev_b32_e32 v6, 16, v47
	v_and_b32_e32 v7, 0xffff0000, v47
	v_lshlrev_b32_e32 v44, 16, v40
	v_and_b32_e32 v45, 0xffff0000, v40
	v_lshlrev_b32_e32 v40, 16, v41
	v_and_b32_e32 v41, 0xffff0000, v41
	v_lshlrev_b32_e32 v46, 16, v42
	v_and_b32_e32 v47, 0xffff0000, v42
	v_lshlrev_b32_e32 v42, 16, v43
	v_and_b32_e32 v43, 0xffff0000, v43
	v_pk_fma_f32 v[0:1], v[140:141], v[116:117], v[0:1] op_sel_hi:[1,0,1]
	v_pk_fma_f32 v[2:3], v[138:139], v[116:117], v[2:3] op_sel_hi:[1,0,1]
	v_pk_fma_f32 v[4:5], v[136:137], v[116:117], v[4:5] op_sel_hi:[1,0,1]
	v_pk_fma_f32 v[6:7], v[134:135], v[116:117], v[6:7] op_sel_hi:[1,0,1]
	v_pk_fma_f32 v[8:9], v[8:9], v[116:117], v[44:45] op_sel_hi:[1,0,1]
	v_pk_fma_f32 v[10:11], v[10:11], v[116:117], v[40:41] op_sel_hi:[1,0,1]
	v_pk_fma_f32 v[12:13], v[12:13], v[116:117], v[46:47] op_sel_hi:[1,0,1]
	v_pk_fma_f32 v[14:15], v[14:15], v[116:117], v[42:43] op_sel_hi:[1,0,1]
	ds_read_b128 v[44:47], v115 offset:2048
	ds_read_b128 v[138:141], v115 offset:3072
	v_add_u32_e32 v146, 8, v201
	v_min_u32_e32 v146, 0x7f, v146
	v_lshl_add_u32 v146, v146, 17, v128
	v_add_u32_e32 v147, 0x1000, v146
	s_waitcnt vmcnt(43)
	s_waitcnt lgkmcnt(3)
	v_mfma_f32_32x32x16_bf16 v[0:15], v[148:151], v[24:27], v[0:15]
	global_load_dwordx4 v[148:151], v146, s[100:101]
	v_lshl_add_u64 v[144:145], v[96:97], 0, s[6:7]
	s_min_u32 s6, s29, 0x72
	s_add_i32 s6, s26, s6
	s_lshl_b32 s6, s6, 2
	s_or_b32 s6, s6, s13
	s_waitcnt vmcnt(43)
	s_waitcnt lgkmcnt(2)
	v_mfma_f32_32x32x16_bf16 v[16:31], v[152:155], v[28:31], 0
	global_load_dwordx4 v[152:155], v146, s[100:101] offset:1024
	s_waitcnt vmcnt(43)
	s_waitcnt lgkmcnt(1)
	v_mfma_f32_32x32x16_bf16 v[0:15], v[156:159], v[44:47], v[0:15]
	global_load_dwordx4 v[156:159], v146, s[100:101] offset:2048
	s_waitcnt vmcnt(43)
	s_waitcnt lgkmcnt(0)
	v_mfma_f32_32x32x16_bf16 v[16:31], v[160:163], v[138:141], v[16:31]
	global_load_dwordx4 v[160:163], v146, s[100:101] offset:3072
	ds_read_b128 v[44:47], v115 offset:4096
	ds_read_b128 v[138:141], v115 offset:5120
	s_waitcnt vmcnt(43)
	s_waitcnt lgkmcnt(1)
	v_mfma_f32_32x32x16_bf16 v[0:15], v[164:167], v[44:47], v[0:15]
	global_load_dwordx4 v[164:167], v147, s[100:101]
	v_lshl_add_u64 v[40:41], s[92:93], 0, v[102:103]
	v_add_co_u32_e32 v142, vcc, s28, v40
	v_lshl_add_u64 v[102:103], v[102:103], 0, s[8:9]
	s_nop 0
	v_addc_co_u32_e32 v143, vcc, 0, v41, vcc
	s_waitcnt vmcnt(43)
	s_waitcnt lgkmcnt(0)
	v_mfma_f32_32x32x16_bf16 v[16:31], v[168:171], v[138:141], v[16:31]
	global_load_dwordx4 v[168:171], v147, s[100:101] offset:1024
	ds_read_b128 v[40:43], v123 offset:22528
	ds_read_b128 v[44:47], v115 offset:6144
	ds_read_b128 v[134:137], v123 offset:23552
	ds_read_b128 v[138:141], v115 offset:7168
	s_waitcnt lgkmcnt(2)
	v_mfma_f32_32x32x16_bf16 v[0:15], v[40:43], v[44:47], v[0:15]
	v_mov_b32_e32 v40, s30
	s_lshl_b32 s30, s6, 2
	s_lshl_b32 s6, s6, 15
	s_waitcnt lgkmcnt(0)
	v_mfma_f32_32x32x16_bf16 v[16:31], v[134:137], v[138:141], v[16:31]
	s_nop 11
	v_pk_add_f32 v[134:135], v[6:7], v[22:23]
	v_pk_add_f32 v[136:137], v[4:5], v[20:21]
	v_pk_add_f32 v[138:139], v[2:3], v[18:19]
	v_pk_add_f32 v[140:141], v[0:1], v[16:17]
	v_pk_add_f32 v[14:15], v[14:15], v[30:31]
	v_pk_add_f32 v[12:13], v[12:13], v[28:29]
	v_pk_add_f32 v[10:11], v[10:11], v[26:27]
	v_pk_add_f32 v[8:9], v[8:9], v[24:25]
	v_cvt_pk_bf16_f32 v0, v140, v141
	v_cvt_pk_bf16_f32 v1, v138, v139
	v_cvt_pk_bf16_f32 v2, v136, v137
	v_cvt_pk_bf16_f32 v3, v134, v135
	v_cvt_pk_bf16_f32 v4, v8, v9
	v_cvt_pk_bf16_f32 v5, v10, v11
	v_cvt_pk_bf16_f32 v6, v12, v13
	v_cvt_pk_bf16_f32 v7, v14, v15
	ds_write_b128 v117, v[0:3] offset:8192
	ds_write_b128 v117, v[4:7] offset:9216
	global_store_dwordx4 v[142:143], v[0:3], off
	global_store_dwordx4 v[142:143], v[4:7], off offset:1024
	s_waitcnt lgkmcnt(0)
	s_barrier
	global_load_dword v116, v40, s[4:5]
	global_load_dwordx4 v[44:47], v[144:145], off
	s_nop 0
	global_load_dwordx4 v[40:43], v[144:145], off offset:1024
	ds_read_b128 v[24:27], v115 offset:8192
	ds_read_b128 v[28:31], v115 offset:9216
	v_lshlrev_b32_e32 v0, 16, v52
	v_and_b32_e32 v1, 0xffff0000, v52
	v_lshlrev_b32_e32 v2, 16, v53
	v_and_b32_e32 v3, 0xffff0000, v53
	v_lshlrev_b32_e32 v4, 16, v54
	v_and_b32_e32 v5, 0xffff0000, v54
	v_lshlrev_b32_e32 v6, 16, v55
	v_and_b32_e32 v7, 0xffff0000, v55
	v_lshlrev_b32_e32 v52, 16, v48
	v_and_b32_e32 v53, 0xffff0000, v48
	v_lshlrev_b32_e32 v48, 16, v49
	v_and_b32_e32 v49, 0xffff0000, v49
	v_lshlrev_b32_e32 v54, 16, v50
	v_and_b32_e32 v55, 0xffff0000, v50
	v_lshlrev_b32_e32 v50, 16, v51
	v_and_b32_e32 v51, 0xffff0000, v51
	v_pk_fma_f32 v[0:1], v[140:141], v[118:119], v[0:1] op_sel_hi:[1,0,1]
	v_pk_fma_f32 v[2:3], v[138:139], v[118:119], v[2:3] op_sel_hi:[1,0,1]
	v_pk_fma_f32 v[4:5], v[136:137], v[118:119], v[4:5] op_sel_hi:[1,0,1]
	v_pk_fma_f32 v[6:7], v[134:135], v[118:119], v[6:7] op_sel_hi:[1,0,1]
	v_pk_fma_f32 v[8:9], v[8:9], v[118:119], v[52:53] op_sel_hi:[1,0,1]
	v_pk_fma_f32 v[10:11], v[10:11], v[118:119], v[48:49] op_sel_hi:[1,0,1]
	v_pk_fma_f32 v[12:13], v[12:13], v[118:119], v[54:55] op_sel_hi:[1,0,1]
	v_pk_fma_f32 v[14:15], v[14:15], v[118:119], v[50:51] op_sel_hi:[1,0,1]
	ds_read_b128 v[52:55], v115 offset:10240
	ds_read_b128 v[138:141], v115 offset:11264
	v_add_u32_e32 v146, 9, v201
	v_min_u32_e32 v146, 0x7f, v146
	v_lshl_add_u32 v146, v146, 17, v128
	v_add_u32_e32 v147, 0x1000, v146
	s_waitcnt vmcnt(43)
; __device__ __forceinline__ void scan_step(const ScanB& p, f32x16& acc, unsigned char* ws, LAS unsigned char* lds, int bh, int n, int cur, int td, int te, int lane) {
;     const int item = scan_item(bh, n);
;     v4u b0 = p.bn[0], b1 = p.bn[1]; float egl = p.egl;
;     asm volatile("" : "+v"(egl)); asm volatile("" : "+v"(b0)); asm volatile("" : "+v"(b1));
;     f32x16 bv16; ans_unpack(b0, b1, bv16);
; #pragma unroll
;     for (int r = 0; r < 16; ++r) acc[r] = acc[r] * egl + bv16[r];
;     const LAS unsigned char* sb = lds + cur * 8192 + lane * 16;
;     const LAS unsigned char* sa = lds + SC_RING + (n & 3) * SC_SLOT + td * 8192 + lane * 16;
;     f32x16 acc2 = zero16();
; #pragma unroll
;     for (int q = 0; q < 8; q += 2) {
;         const bf16x8 a0 = *(const LAS bf16x8*)(sa + 1024 * q), bv0 = *(const LAS bf16x8*)(sb + 1024 * q);
;         const bf16x8 a1 = *(const LAS bf16x8*)(sa + 1024 * (q + 1)), bv1 = *(const LAS bf16x8*)(sb + 1024 * (q + 1));
;         acc = __builtin_amdgcn_mfma_f32_32x32x16_bf16(a0, bv0, acc, 0, 0, 0); acc2 = __builtin_amdgcn_mfma_f32_32x32x16_bf16(a1, bv1, acc2, 0, 0, 0); }
; #pragma unroll
;     for (int r = 0; r < 16; ++r) acc[r] += acc2[r];
;     v4u w0, w1; ans_pack(acc, w0, w1);
;     LAS unsigned char* sn = lds + (cur ^ 1) * 8192 + td * 2048 + lane * 16;
;     *(LAS v4u*)sn = w0; *(LAS v4u*)(sn + 1024) = w1;
;     bf16* So = (bf16*)(ws + WS_BS) + (size_t)item * 16384 + (te * 4 + td) * 1024 + lane * 8;
;     *(v4u*)So = w0; *(v4u*)(So + 512) = w1;
; __device__ __forceinline__ void dn_scan(const Args& a, LAS unsigned char* lds, int wg, int tid, int wave, int lane) {
;     ...
;             scanb_load(p7, ws, bh, n + 7, td, te, lane);  scan_step(p0, acc, ws, lds, bh, n, 0, td, te, lane); WG_BAR();
;             scanb_load(p0, ws, bh, n + 8, td, te, lane);  scan_step(p1, acc, ws, lds, bh, n + 1, 1, td, te, lane); WG_BAR();
;             scanb_load(p1, ws, bh, n + 9, td, te, lane);  scan_step(p2, acc, ws, lds, bh, n + 2, 0, td, te, lane); WG_BAR();
;             scanb_load(p2, ws, bh, n + 10, td, te, lane); scan_step(p3, acc, ws, lds, bh, n + 3, 1, td, te, lane); WG_BAR();
;             scanb_load(p3, ws, bh, n + 11, td, te, lane); scan_step(p4, acc, ws, lds, bh, n + 4, 0, td, te, lane); WG_BAR();
;             scanb_load(p4, ws, bh, n + 12, td, te, lane); scan_step(p5, acc, ws, lds, bh, n + 5, 1, td, te, lane); WG_BAR();
	s_waitcnt lgkmcnt(3)
	v_mfma_f32_32x32x16_bf16 v[0:15], v[172:175], v[24:27], v[0:15]
	global_load_dwordx4 v[172:175], v146, s[100:101]
	v_lshl_add_u64 v[144:145], v[96:97], 0, s[6:7]
	s_min_u32 s6, s29, 0x71
	s_add_i32 s6, s27, s6
	s_lshl_b32 s6, s6, 2
	s_or_b32 s6, s6, s13
	s_waitcnt vmcnt(43)
	s_waitcnt lgkmcnt(2)
	v_mfma_f32_32x32x16_bf16 v[16:31], v[176:179], v[28:31], 0
	global_load_dwordx4 v[176:179], v146, s[100:101] offset:1024
	s_waitcnt vmcnt(43)
	s_waitcnt lgkmcnt(1)
	v_mfma_f32_32x32x16_bf16 v[0:15], v[180:183], v[52:55], v[0:15]
	global_load_dwordx4 v[180:183], v146, s[100:101] offset:2048
	s_waitcnt vmcnt(43)
	s_waitcnt lgkmcnt(0)
	v_mfma_f32_32x32x16_bf16 v[16:31], v[184:187], v[138:141], v[16:31]
	global_load_dwordx4 v[184:187], v146, s[100:101] offset:3072
	ds_read_b128 v[52:55], v115 offset:12288
	ds_read_b128 v[138:141], v115 offset:13312
	s_waitcnt vmcnt(43)
	s_waitcnt lgkmcnt(1)
	v_mfma_f32_32x32x16_bf16 v[0:15], v[188:191], v[52:55], v[0:15]
	global_load_dwordx4 v[188:191], v147, s[100:101]
	v_lshl_add_u64 v[48:49], s[92:93], 0, v[100:101]
	v_add_co_u32_e32 v142, vcc, s28, v48
	v_lshl_add_u64 v[100:101], v[100:101], 0, s[8:9]
	s_nop 0
	v_addc_co_u32_e32 v143, vcc, 0, v49, vcc
	s_waitcnt vmcnt(43)
	s_waitcnt lgkmcnt(0)
	v_mfma_f32_32x32x16_bf16 v[16:31], v[192:195], v[138:141], v[16:31]
	global_load_dwordx4 v[192:195], v147, s[100:101] offset:1024
	ds_read_b128 v[48:51], v121 offset:55296
	ds_read_b128 v[52:55], v115 offset:14336
	ds_read_b128 v[134:137], v121 offset:56320
	ds_read_b128 v[138:141], v115 offset:15360
	s_waitcnt lgkmcnt(2)
	v_mfma_f32_32x32x16_bf16 v[0:15], v[48:51], v[52:55], v[0:15]
	v_mov_b32_e32 v48, s30
	s_lshl_b32 s30, s6, 2
	s_lshl_b32 s6, s6, 15
	s_add_u32 s10, s10, 0x80
	s_addc_u32 s11, s11, 0
	s_cmpk_gt_u32 s29, 0x77
	s_waitcnt lgkmcnt(0)
	v_mfma_f32_32x32x16_bf16 v[16:31], v[134:137], v[138:141], v[16:31]
	s_nop 11
	v_pk_add_f32 v[134:135], v[6:7], v[22:23]
	v_pk_add_f32 v[136:137], v[4:5], v[20:21]
	v_pk_add_f32 v[138:139], v[2:3], v[18:19]
	v_pk_add_f32 v[140:141], v[0:1], v[16:17]
	v_pk_add_f32 v[14:15], v[14:15], v[30:31]
	v_pk_add_f32 v[12:13], v[12:13], v[28:29]
	v_pk_add_f32 v[10:11], v[10:11], v[26:27]
	v_pk_add_f32 v[8:9], v[8:9], v[24:25]
	v_cvt_pk_bf16_f32 v0, v140, v141
	v_cvt_pk_bf16_f32 v1, v138, v139
	v_cvt_pk_bf16_f32 v2, v136, v137
	v_cvt_pk_bf16_f32 v3, v134, v135
	v_cvt_pk_bf16_f32 v4, v8, v9
	v_cvt_pk_bf16_f32 v5, v10, v11
	v_cvt_pk_bf16_f32 v6, v12, v13
	v_cvt_pk_bf16_f32 v7, v14, v15
	ds_write_b128 v119, v[0:3]
	ds_write_b128 v119, v[4:7] offset:1024
	global_store_dwordx4 v[142:143], v[0:3], off
	global_store_dwordx4 v[142:143], v[4:7], off offset:1024
	s_waitcnt lgkmcnt(0)
	s_barrier
	global_load_dword v118, v48, s[4:5]
	global_load_dwordx4 v[52:55], v[144:145], off
	s_nop 0
	global_load_dwordx4 v[48:51], v[144:145], off offset:1024
	ds_read_b128 v[24:27], v115
	ds_read_b128 v[28:31], v115 offset:1024
	v_lshlrev_b32_e32 v0, 16, v72
	v_and_b32_e32 v1, 0xffff0000, v72
	v_lshlrev_b32_e32 v2, 16, v73
	v_and_b32_e32 v3, 0xffff0000, v73
	v_lshlrev_b32_e32 v4, 16, v74
	v_and_b32_e32 v5, 0xffff0000, v74
	v_lshlrev_b32_e32 v6, 16, v75
	v_and_b32_e32 v7, 0xffff0000, v75
	v_lshlrev_b32_e32 v72, 16, v64
	v_and_b32_e32 v73, 0xffff0000, v64
	v_lshlrev_b32_e32 v64, 16, v65
	v_and_b32_e32 v65, 0xffff0000, v65
	v_lshlrev_b32_e32 v74, 16, v66
	v_and_b32_e32 v75, 0xffff0000, v66
	v_lshlrev_b32_e32 v66, 16, v67
	v_and_b32_e32 v67, 0xffff0000, v67
	v_pk_fma_f32 v[0:1], v[140:141], v[120:121], v[0:1] op_sel_hi:[1,0,1]
	v_pk_fma_f32 v[2:3], v[138:139], v[120:121], v[2:3] op_sel_hi:[1,0,1]
	v_pk_fma_f32 v[4:5], v[136:137], v[120:121], v[4:5] op_sel_hi:[1,0,1]
	v_pk_fma_f32 v[6:7], v[134:135], v[120:121], v[6:7] op_sel_hi:[1,0,1]
	v_pk_fma_f32 v[8:9], v[8:9], v[120:121], v[72:73] op_sel_hi:[1,0,1]
	v_pk_fma_f32 v[10:11], v[10:11], v[120:121], v[64:65] op_sel_hi:[1,0,1]
	v_pk_fma_f32 v[12:13], v[12:13], v[120:121], v[74:75] op_sel_hi:[1,0,1]
	v_pk_fma_f32 v[14:15], v[14:15], v[120:121], v[66:67] op_sel_hi:[1,0,1]
	ds_read_b128 v[72:75], v115 offset:2048
	ds_read_b128 v[138:141], v115 offset:3072
	v_add_u32_e32 v146, 10, v201
	v_min_u32_e32 v146, 0x7f, v146
	v_lshl_add_u32 v146, v146, 17, v128
	v_add_u32_e32 v147, 0x1000, v146
	s_waitcnt vmcnt(43)
	s_waitcnt lgkmcnt(3)
	v_mfma_f32_32x32x16_bf16 v[0:15], v[196:199], v[24:27], v[0:15]
	global_load_dwordx4 v[196:199], v146, s[100:101]
	v_lshl_add_u64 v[142:143], v[96:97], 0, s[6:7]
	s_waitcnt vmcnt(43)
	s_waitcnt lgkmcnt(2)
	v_mfma_f32_32x32x16_bf16 v[16:31], v[208:211], v[28:31], 0
	global_load_dwordx4 v[208:211], v146, s[100:101] offset:1024
	s_waitcnt vmcnt(43)
	s_waitcnt lgkmcnt(1)
	v_mfma_f32_32x32x16_bf16 v[0:15], v[212:215], v[72:75], v[0:15]
	global_load_dwordx4 v[212:215], v146, s[100:101] offset:2048
	s_waitcnt vmcnt(43)
	s_waitcnt lgkmcnt(0)
	v_mfma_f32_32x32x16_bf16 v[16:31], v[216:219], v[138:141], v[16:31]
	global_load_dwordx4 v[216:219], v146, s[100:101] offset:3072
	ds_read_b128 v[72:75], v115 offset:4096
	ds_read_b128 v[138:141], v115 offset:5120
	s_waitcnt vmcnt(43)
	s_waitcnt lgkmcnt(1)
	v_mfma_f32_32x32x16_bf16 v[0:15], v[220:223], v[72:75], v[0:15]
	global_load_dwordx4 v[220:223], v147, s[100:101]
	v_lshl_add_u64 v[64:65], s[92:93], 0, v[98:99]
	v_add_co_u32_e32 v120, vcc, s28, v64
	v_lshl_add_u64 v[98:99], v[98:99], 0, s[8:9]
	s_nop 0
	v_addc_co_u32_e32 v121, vcc, 0, v65, vcc
	s_waitcnt vmcnt(43)
	s_waitcnt lgkmcnt(0)
	v_mfma_f32_32x32x16_bf16 v[16:31], v[224:227], v[138:141], v[16:31]
	global_load_dwordx4 v[224:227], v147, s[100:101] offset:1024
	ds_read_b128 v[64:67], v125 offset:6144
	ds_read_b128 v[72:75], v115 offset:6144
	ds_read_b128 v[134:137], v125 offset:7168
	ds_read_b128 v[138:141], v115 offset:7168
	s_waitcnt lgkmcnt(2)
	v_mfma_f32_32x32x16_bf16 v[0:15], v[64:67], v[72:75], v[0:15]
	v_mov_b32_e32 v64, s30
	s_mov_b32 s30, s29
	s_waitcnt lgkmcnt(0)
	v_mfma_f32_32x32x16_bf16 v[16:31], v[134:137], v[138:141], v[16:31]
	s_nop 11
	v_pk_add_f32 v[134:135], v[6:7], v[22:23]
	v_pk_add_f32 v[136:137], v[4:5], v[20:21]
	v_pk_add_f32 v[138:139], v[2:3], v[18:19]
	v_pk_add_f32 v[140:141], v[0:1], v[16:17]
	v_pk_add_f32 v[14:15], v[14:15], v[30:31]
	v_pk_add_f32 v[12:13], v[12:13], v[28:29]
	v_pk_add_f32 v[10:11], v[10:11], v[26:27]
	v_pk_add_f32 v[8:9], v[8:9], v[24:25]
	v_cvt_pk_bf16_f32 v0, v140, v141
	v_cvt_pk_bf16_f32 v1, v138, v139
	v_cvt_pk_bf16_f32 v2, v136, v137
	v_cvt_pk_bf16_f32 v3, v134, v135
	v_cvt_pk_bf16_f32 v4, v8, v9
	v_cvt_pk_bf16_f32 v5, v10, v11
	v_cvt_pk_bf16_f32 v6, v12, v13
	v_cvt_pk_bf16_f32 v7, v14, v15
	ds_write_b128 v117, v[0:3] offset:8192
	ds_write_b128 v117, v[4:7] offset:9216
	global_store_dwordx4 v[120:121], v[0:3], off
	global_store_dwordx4 v[120:121], v[4:7], off offset:1024
	s_waitcnt lgkmcnt(0)
	s_barrier
; __device__ __forceinline__ void scan_step(const ScanB& p, f32x16& acc, unsigned char* ws, LAS unsigned char* lds, int bh, int n, int cur, int td, int te, int lane) {
;     const int item = scan_item(bh, n);
;     v4u b0 = p.bn[0], b1 = p.bn[1]; float egl = p.egl;
;     asm volatile("" : "+v"(egl)); asm volatile("" : "+v"(b0)); asm volatile("" : "+v"(b1));
;     f32x16 bv16; ans_unpack(b0, b1, bv16);
; #pragma unroll
;     for (int r = 0; r < 16; ++r) acc[r] = acc[r] * egl + bv16[r];
;     const LAS unsigned char* sb = lds + cur * 8192 + lane * 16;
;     const LAS unsigned char* sa = lds + SC_RING + (n & 3) * SC_SLOT + td * 8192 + lane * 16;
;     f32x16 acc2 = zero16();
; #pragma unroll
;     for (int q = 0; q < 8; q += 2) {
;         const bf16x8 a0 = *(const LAS bf16x8*)(sa + 1024 * q), bv0 = *(const LAS bf16x8*)(sb + 1024 * q);
;         const bf16x8 a1 = *(const LAS bf16x8*)(sa + 1024 * (q + 1)), bv1 = *(const LAS bf16x8*)(sb + 1024 * (q + 1));
;         acc = __builtin_amdgcn_mfma_f32_32x32x16_bf16(a0, bv0, acc, 0, 0, 0); acc2 = __builtin_amdgcn_mfma_f32_32x32x16_bf16(a1, bv1, acc2, 0, 0, 0); }
; #pragma unroll
;     for (int r = 0; r < 16; ++r) acc[r] += acc2[r];
;     v4u w0, w1; ans_pack(acc, w0, w1);
;     LAS unsigned char* sn = lds + (cur ^ 1) * 8192 + td * 2048 + lane * 16;
;     *(LAS v4u*)sn = w0; *(LAS v4u*)(sn + 1024) = w1;
;     bf16* So = (bf16*)(ws + WS_BS) + (size_t)item * 16384 + (te * 4 + td) * 1024 + lane * 8;
;     *(v4u*)So = w0; *(v4u*)(So + 512) = w1;
; __device__ __forceinline__ void dn_scan(const Args& a, LAS unsigned char* lds, int wg, int tid, int wave, int lane) {
;     ...
;             scanb_load(p7, ws, bh, n + 7, td, te, lane);  scan_step(p0, acc, ws, lds, bh, n, 0, td, te, lane); WG_BAR();
;             scanb_load(p0, ws, bh, n + 8, td, te, lane);  scan_step(p1, acc, ws, lds, bh, n + 1, 1, td, te, lane); WG_BAR();
;             scanb_load(p1, ws, bh, n + 9, td, te, lane);  scan_step(p2, acc, ws, lds, bh, n + 2, 0, td, te, lane); WG_BAR();
;             scanb_load(p2, ws, bh, n + 10, td, te, lane); scan_step(p3, acc, ws, lds, bh, n + 3, 1, td, te, lane); WG_BAR();
;             scanb_load(p3, ws, bh, n + 11, td, te, lane); scan_step(p4, acc, ws, lds, bh, n + 4, 0, td, te, lane); WG_BAR();
;             scanb_load(p4, ws, bh, n + 12, td, te, lane); scan_step(p5, acc, ws, lds, bh, n + 5, 1, td, te, lane); WG_BAR();
	global_load_dword v120, v64, s[4:5]
	global_load_dwordx4 v[72:75], v[142:143], off
	s_nop 0
	global_load_dwordx4 v[64:67], v[142:143], off offset:1024
	ds_read_b128 v[24:27], v115 offset:8192
	ds_read_b128 v[28:31], v115 offset:9216
	v_lshlrev_b32_e32 v0, 16, v92
	v_and_b32_e32 v1, 0xffff0000, v92
	v_lshlrev_b32_e32 v2, 16, v93
	v_and_b32_e32 v3, 0xffff0000, v93
	v_lshlrev_b32_e32 v4, 16, v94
	v_and_b32_e32 v5, 0xffff0000, v94
	v_lshlrev_b32_e32 v6, 16, v95
	v_and_b32_e32 v7, 0xffff0000, v95
	v_lshlrev_b32_e32 v92, 16, v88
	v_and_b32_e32 v93, 0xffff0000, v88
	v_lshlrev_b32_e32 v88, 16, v89
	v_and_b32_e32 v89, 0xffff0000, v89
	v_lshlrev_b32_e32 v94, 16, v90
	v_and_b32_e32 v95, 0xffff0000, v90
	v_lshlrev_b32_e32 v90, 16, v91
	v_and_b32_e32 v91, 0xffff0000, v91
	v_pk_fma_f32 v[0:1], v[140:141], v[132:133], v[0:1] op_sel_hi:[1,0,1]
	v_pk_fma_f32 v[2:3], v[138:139], v[132:133], v[2:3] op_sel_hi:[1,0,1]
	v_pk_fma_f32 v[4:5], v[136:137], v[132:133], v[4:5] op_sel_hi:[1,0,1]
	v_pk_fma_f32 v[6:7], v[134:135], v[132:133], v[6:7] op_sel_hi:[1,0,1]
	v_pk_fma_f32 v[8:9], v[8:9], v[132:133], v[92:93] op_sel_hi:[1,0,1]
	v_pk_fma_f32 v[10:11], v[10:11], v[132:133], v[88:89] op_sel_hi:[1,0,1]
	v_pk_fma_f32 v[12:13], v[12:13], v[132:133], v[94:95] op_sel_hi:[1,0,1]
	v_pk_fma_f32 v[14:15], v[14:15], v[132:133], v[90:91] op_sel_hi:[1,0,1]
	ds_read_b128 v[92:95], v115 offset:10240
	ds_read_b128 v[136:139], v115 offset:11264
	v_add_u32_e32 v146, 11, v201
	v_min_u32_e32 v146, 0x7f, v146
	v_lshl_add_u32 v146, v146, 17, v128
	v_add_u32_e32 v147, 0x1000, v146
	s_waitcnt vmcnt(43)
	s_waitcnt lgkmcnt(3)
	v_mfma_f32_32x32x16_bf16 v[0:15], v[228:231], v[24:27], v[0:15]
	global_load_dwordx4 v[228:231], v146, s[100:101]
	s_waitcnt vmcnt(43)
	s_waitcnt lgkmcnt(2)
	v_mfma_f32_32x32x16_bf16 v[16:31], v[232:235], v[28:31], 0
	global_load_dwordx4 v[232:235], v146, s[100:101] offset:1024
	s_waitcnt vmcnt(43)
	s_waitcnt lgkmcnt(1)
	v_mfma_f32_32x32x16_bf16 v[0:15], v[236:239], v[92:95], v[0:15]
	global_load_dwordx4 v[236:239], v146, s[100:101] offset:2048
	s_waitcnt vmcnt(43)
	s_waitcnt lgkmcnt(0)
	v_mfma_f32_32x32x16_bf16 v[16:31], v[240:243], v[136:139], v[16:31]
	global_load_dwordx4 v[240:243], v146, s[100:101] offset:3072
	ds_read_b128 v[92:95], v115 offset:12288
	ds_read_b128 v[136:139], v115 offset:13312
	s_waitcnt vmcnt(43)
	s_waitcnt lgkmcnt(1)
	v_mfma_f32_32x32x16_bf16 v[0:15], v[244:247], v[92:95], v[0:15]
	global_load_dwordx4 v[244:247], v147, s[100:101]
	s_waitcnt vmcnt(43)
	s_waitcnt lgkmcnt(0)
	v_mfma_f32_32x32x16_bf16 v[16:31], v[248:251], v[136:139], v[16:31]
	global_load_dwordx4 v[248:251], v147, s[100:101] offset:1024
	ds_read_b128 v[88:91], v127 offset:6144
	ds_read_b128 v[92:95], v115 offset:14336
	ds_read_b128 v[132:135], v127 offset:7168
	ds_read_b128 v[136:139], v115 offset:15360
	s_waitcnt lgkmcnt(2)
	v_mfma_f32_32x32x16_bf16 v[0:15], v[88:91], v[92:95], v[0:15]
	s_waitcnt lgkmcnt(0)
	v_mfma_f32_32x32x16_bf16 v[16:31], v[132:135], v[136:139], v[16:31]
	s_nop 11
	v_pk_add_f32 v[6:7], v[6:7], v[22:23]
	v_pk_add_f32 v[4:5], v[4:5], v[20:21]
	v_pk_add_f32 v[2:3], v[2:3], v[18:19]
	v_pk_add_f32 v[0:1], v[0:1], v[16:17]
	v_pk_add_f32 v[14:15], v[14:15], v[30:31]
	v_pk_add_f32 v[12:13], v[12:13], v[28:29]
	v_pk_add_f32 v[10:11], v[10:11], v[26:27]
	v_pk_add_f32 v[8:9], v[8:9], v[24:25]
	v_cvt_pk_bf16_f32 v16, v0, v1
	v_cvt_pk_bf16_f32 v17, v2, v3
	v_cvt_pk_bf16_f32 v18, v4, v5
	v_cvt_pk_bf16_f32 v19, v6, v7
	v_cvt_pk_bf16_f32 v20, v8, v9
	v_cvt_pk_bf16_f32 v21, v10, v11
	v_cvt_pk_bf16_f32 v22, v12, v13
	v_cvt_pk_bf16_f32 v23, v14, v15
	ds_write_b128 v119, v[16:19]
	ds_write_b128 v119, v[20:23] offset:1024
	global_store_dwordx4 v[130:131], v[16:19], off
	global_store_dwordx4 v[130:131], v[20:23], off offset:1024
	s_waitcnt lgkmcnt(0)
	s_barrier
	s_cbranch_scc0 .LBB0_1068
